# main epilogue fast paths: lanes permuted (ds_bpermute) so each 4 lanes store 64 contiguous bytes; V^T tiles through 8x8 lane transpose; branch-merge epilogue
# speedup vs baseline: 1.0176x; 1.0104x over previous
.LBB0_372:
	s_add_u32 s8, s6, 0xfff80080
	s_addc_u32 s9, s7, -1
	s_add_i32 s21, 0, 0x10000
	v_add_u32_e32 v143, s21, v167
	ds_read_b128 v[148:151], v143
	ds_read_b128 v[152:155], v143 offset:1024
	ds_read_b128 v[156:159], v143 offset:2048
	ds_read_b128 v[160:163], v143 offset:3072
	s_cmp_eq_u32 s20, 28
	s_cselect_b32 s11, s17, s9
	s_cselect_b32 s10, s16, s8
	s_cselect_b32 s9, s19, s15
	s_cselect_b32 s8, s18, s13
	v_lshl_add_u64 v[164:165], s[6:7], 0, v[138:139]
	s_add_i32 m0, s40, 0xc000
	ds_read_b128 v[172:175], v171
	ds_read_b128 v[180:183], v171 offset:1024
	ds_read_b128 v[184:187], v171 offset:2048
	ds_read_b128 v[188:191], v171 offset:3072
	ds_read_b128 v[192:195], v171 offset:4096
	ds_read_b128 v[196:199], v171 offset:5120
	ds_read_b128 v[200:203], v171 offset:6144
	ds_read_b128 v[204:207], v171 offset:7168
	global_load_lds_dwordx4 v[164:165], off
	v_lshl_add_u64 v[164:165], s[6:7], 0, v[140:141]
	s_add_i32 m0, s40, 0xe000
	s_nop 0
	global_load_lds_dwordx4 v[164:165], off
	s_waitcnt lgkmcnt(8)
	s_barrier
	s_waitcnt lgkmcnt(0)
	s_setprio 1
	s_waitcnt lgkmcnt(0)
	v_mfma_f32_16x16x32_bf16 v[126:129], v[148:151], v[172:175], v[126:129]
	v_mfma_f32_16x16x32_bf16 v[122:125], v[156:159], v[172:175], v[122:125]
	v_mfma_f32_16x16x32_bf16 v[110:113], v[148:151], v[184:187], v[110:113]
	v_mfma_f32_16x16x32_bf16 v[106:109], v[156:159], v[184:187], v[106:109]
	v_mfma_f32_16x16x32_bf16 v[94:97], v[148:151], v[192:195], v[94:97]
	v_mfma_f32_16x16x32_bf16 v[90:93], v[156:159], v[192:195], v[90:93]
	v_mfma_f32_16x16x32_bf16 v[78:81], v[148:151], v[200:203], v[78:81]
	v_mfma_f32_16x16x32_bf16 v[74:77], v[156:159], v[200:203], v[74:77]
	v_mfma_f32_16x16x32_bf16 v[126:129], v[152:155], v[180:183], v[126:129]
	v_mfma_f32_16x16x32_bf16 v[122:125], v[160:163], v[180:183], v[122:125]
	v_mfma_f32_16x16x32_bf16 v[110:113], v[152:155], v[188:191], v[110:113]
	v_mfma_f32_16x16x32_bf16 v[106:109], v[160:163], v[188:191], v[106:109]
	v_mfma_f32_16x16x32_bf16 v[94:97], v[152:155], v[196:199], v[94:97]
	v_mfma_f32_16x16x32_bf16 v[90:93], v[160:163], v[196:199], v[90:93]
	v_mfma_f32_16x16x32_bf16 v[78:81], v[152:155], v[204:207], v[78:81]
	v_mfma_f32_16x16x32_bf16 v[74:77], v[160:163], v[204:207], v[74:77]
	s_setprio 0
	s_barrier
	s_add_i32 s24, 0, 0x14000
	s_add_i32 s21, s21, s39
	v_add_u32_e32 v143, s24, v167
	v_lshl_add_u64 v[164:165], s[8:9], 0, v[134:135]
	s_mov_b32 m0, s21
	ds_read_b128 v[208:211], v143
	ds_read_b128 v[212:215], v143 offset:1024
	ds_read_b128 v[216:219], v143 offset:2048
	ds_read_b128 v[220:223], v143 offset:3072
	global_load_lds_dwordx4 v[164:165], off
	v_lshl_add_u64 v[176:177], s[8:9], 0, v[130:131]
	s_add_i32 m0, s21, 0x2000
	s_nop 0
	global_load_lds_dwordx4 v[176:177], off
	s_barrier
	s_waitcnt lgkmcnt(0)
	s_setprio 1
	s_waitcnt lgkmcnt(0)
	v_mfma_f32_16x16x32_bf16 v[118:121], v[208:211], v[172:175], v[118:121]
	v_mfma_f32_16x16x32_bf16 v[114:117], v[216:219], v[172:175], v[114:117]
	v_mfma_f32_16x16x32_bf16 v[102:105], v[208:211], v[184:187], v[102:105]
	v_mfma_f32_16x16x32_bf16 v[98:101], v[216:219], v[184:187], v[98:101]
	v_mfma_f32_16x16x32_bf16 v[86:89], v[208:211], v[192:195], v[86:89]
	v_mfma_f32_16x16x32_bf16 v[82:85], v[216:219], v[192:195], v[82:85]
	v_mfma_f32_16x16x32_bf16 v[70:73], v[208:211], v[200:203], v[70:73]
	v_mfma_f32_16x16x32_bf16 v[66:69], v[216:219], v[200:203], v[66:69]
	v_mfma_f32_16x16x32_bf16 v[118:121], v[212:215], v[180:183], v[118:121]
	v_mfma_f32_16x16x32_bf16 v[114:117], v[220:223], v[180:183], v[114:117]
	v_mfma_f32_16x16x32_bf16 v[102:105], v[212:215], v[188:191], v[102:105]
	v_mfma_f32_16x16x32_bf16 v[98:101], v[220:223], v[188:191], v[98:101]
	v_mfma_f32_16x16x32_bf16 v[86:89], v[212:215], v[196:199], v[86:89]
	v_mfma_f32_16x16x32_bf16 v[82:85], v[220:223], v[196:199], v[82:85]
	v_mfma_f32_16x16x32_bf16 v[70:73], v[212:215], v[204:207], v[70:73]
	v_mfma_f32_16x16x32_bf16 v[66:69], v[220:223], v[204:207], v[66:69]
	s_setprio 0
	s_mov_b32 m0, s40
	v_lshl_add_u64 v[224:225], s[10:11], 0, v[136:137]
	s_barrier
	ds_read_b128 v[172:175], v171 offset:16384
	ds_read_b128 v[180:183], v171 offset:17408
	ds_read_b128 v[184:187], v171 offset:18432
	ds_read_b128 v[188:191], v171 offset:19456
	ds_read_b128 v[192:195], v171 offset:20480
	ds_read_b128 v[196:199], v171 offset:21504
	ds_read_b128 v[200:203], v171 offset:22528
	ds_read_b128 v[204:207], v171 offset:23552
	global_load_lds_dwordx4 v[224:225], off
	v_lshl_add_u64 v[236:237], s[10:11], 0, v[132:133]
	s_mov_b32 m0, s41
	s_nop 0
	global_load_lds_dwordx4 v[236:237], off
	s_barrier
	s_waitcnt lgkmcnt(0)
	s_setprio 1
	s_waitcnt lgkmcnt(0)
	v_mfma_f32_16x16x32_bf16 v[62:65], v[148:151], v[172:175], v[62:65]
	v_mfma_f32_16x16x32_bf16 v[58:61], v[156:159], v[172:175], v[58:61]
	v_mfma_f32_16x16x32_bf16 v[46:49], v[148:151], v[184:187], v[46:49]
	v_mfma_f32_16x16x32_bf16 v[42:45], v[156:159], v[184:187], v[42:45]
	v_mfma_f32_16x16x32_bf16 v[28:31], v[148:151], v[192:195], v[28:31]
	v_mfma_f32_16x16x32_bf16 v[24:27], v[156:159], v[192:195], v[24:27]
	v_mfma_f32_16x16x32_bf16 v[12:15], v[148:151], v[200:203], v[12:15]
	v_mfma_f32_16x16x32_bf16 v[8:11], v[156:159], v[200:203], v[8:11]
	v_mfma_f32_16x16x32_bf16 v[62:65], v[152:155], v[180:183], v[62:65]
	v_mfma_f32_16x16x32_bf16 v[58:61], v[160:163], v[180:183], v[58:61]
	v_mfma_f32_16x16x32_bf16 v[46:49], v[152:155], v[188:191], v[46:49]
	v_mfma_f32_16x16x32_bf16 v[42:45], v[160:163], v[188:191], v[42:45]
	v_mfma_f32_16x16x32_bf16 v[28:31], v[152:155], v[196:199], v[28:31]
	v_mfma_f32_16x16x32_bf16 v[24:27], v[160:163], v[196:199], v[24:27]
	v_mfma_f32_16x16x32_bf16 v[12:15], v[152:155], v[204:207], v[12:15]
	v_mfma_f32_16x16x32_bf16 v[8:11], v[160:163], v[204:207], v[8:11]
	s_setprio 0
	s_barrier
	s_add_u32 s22, s8, 0x80000
	s_addc_u32 s23, s9, 0
	s_add_i32 s21, s24, s39
	v_lshl_add_u64 v[148:149], s[22:23], 0, v[134:135]
	s_mov_b32 m0, s21
	s_nop 0
	global_load_lds_dwordx4 v[148:149], off
	v_lshl_add_u64 v[148:149], s[22:23], 0, v[130:131]
	s_add_i32 m0, s21, 0x2000
	s_nop 0
	global_load_lds_dwordx4 v[148:149], off
	s_waitcnt vmcnt(6)
	s_barrier
	s_setprio 1
	v_mfma_f32_16x16x32_bf16 v[54:57], v[208:211], v[172:175], v[54:57]
	v_mfma_f32_16x16x32_bf16 v[50:53], v[216:219], v[172:175], v[50:53]
	v_mfma_f32_16x16x32_bf16 v[38:41], v[208:211], v[184:187], v[38:41]
	v_mfma_f32_16x16x32_bf16 v[34:37], v[216:219], v[184:187], v[34:37]
	v_mfma_f32_16x16x32_bf16 v[20:23], v[208:211], v[192:195], v[20:23]
	v_mfma_f32_16x16x32_bf16 v[16:19], v[216:219], v[192:195], v[16:19]
	v_mfma_f32_16x16x32_bf16 v[4:7], v[208:211], v[200:203], v[4:7]
	v_mfma_f32_16x16x32_bf16 v[0:3], v[216:219], v[200:203], v[0:3]
	v_mfma_f32_16x16x32_bf16 v[54:57], v[212:215], v[180:183], v[54:57]
	v_mfma_f32_16x16x32_bf16 v[50:53], v[220:223], v[180:183], v[50:53]
	v_mfma_f32_16x16x32_bf16 v[38:41], v[212:215], v[188:191], v[38:41]
	v_mfma_f32_16x16x32_bf16 v[34:37], v[220:223], v[188:191], v[34:37]
	v_mfma_f32_16x16x32_bf16 v[20:23], v[212:215], v[196:199], v[20:23]
	v_mfma_f32_16x16x32_bf16 v[16:19], v[220:223], v[196:199], v[16:19]
	v_mfma_f32_16x16x32_bf16 v[4:7], v[212:215], v[204:207], v[4:7]
	v_mfma_f32_16x16x32_bf16 v[0:3], v[220:223], v[204:207], v[0:3]
	s_setprio 0
	s_add_i32 s21, 0, 0x18000
	v_add_u32_e32 v143, s21, v167
	s_barrier
	ds_read_b128 v[148:151], v143
	ds_read_b128 v[152:155], v143 offset:1024
	ds_read_b128 v[156:159], v143 offset:2048
	ds_read_b128 v[160:163], v143 offset:3072
	s_add_u32 s10, s10, 0x80000
	s_addc_u32 s11, s11, 0
	s_mov_b32 m0, s42
	v_lshl_add_u64 v[208:209], s[10:11], 0, v[136:137]
	ds_read_b128 v[172:175], v171 offset:32768
	ds_read_b128 v[180:183], v171 offset:33792
	ds_read_b128 v[184:187], v171 offset:34816
	ds_read_b128 v[188:191], v171 offset:35840
	ds_read_b128 v[192:195], v171 offset:36864
	ds_read_b128 v[196:199], v171 offset:37888
	ds_read_b128 v[200:203], v171 offset:38912
	ds_read_b128 v[204:207], v171 offset:39936
	global_load_lds_dwordx4 v[208:209], off
	v_lshl_add_u64 v[208:209], s[10:11], 0, v[132:133]
	s_mov_b32 m0, s43
	s_nop 0
	global_load_lds_dwordx4 v[208:209], off
	s_waitcnt lgkmcnt(8)
	s_barrier
	s_waitcnt lgkmcnt(0)
	s_setprio 1
	s_waitcnt lgkmcnt(0)
	v_mfma_f32_16x16x32_bf16 v[126:129], v[148:151], v[172:175], v[126:129]
	v_mfma_f32_16x16x32_bf16 v[122:125], v[156:159], v[172:175], v[122:125]
	v_mfma_f32_16x16x32_bf16 v[110:113], v[148:151], v[184:187], v[110:113]
	v_mfma_f32_16x16x32_bf16 v[106:109], v[156:159], v[184:187], v[106:109]
	v_mfma_f32_16x16x32_bf16 v[94:97], v[148:151], v[192:195], v[94:97]
	v_mfma_f32_16x16x32_bf16 v[90:93], v[156:159], v[192:195], v[90:93]
	v_mfma_f32_16x16x32_bf16 v[78:81], v[148:151], v[200:203], v[78:81]
	v_mfma_f32_16x16x32_bf16 v[74:77], v[156:159], v[200:203], v[74:77]
	v_mfma_f32_16x16x32_bf16 v[126:129], v[152:155], v[180:183], v[126:129]
	v_mfma_f32_16x16x32_bf16 v[122:125], v[160:163], v[180:183], v[122:125]
	v_mfma_f32_16x16x32_bf16 v[110:113], v[152:155], v[188:191], v[110:113]
	v_mfma_f32_16x16x32_bf16 v[106:109], v[160:163], v[188:191], v[106:109]
	v_mfma_f32_16x16x32_bf16 v[94:97], v[152:155], v[196:199], v[94:97]
	v_mfma_f32_16x16x32_bf16 v[90:93], v[160:163], v[196:199], v[90:93]
	v_mfma_f32_16x16x32_bf16 v[78:81], v[152:155], v[204:207], v[78:81]
	v_mfma_f32_16x16x32_bf16 v[74:77], v[160:163], v[204:207], v[74:77]
	s_setprio 0
	s_barrier
	s_add_i32 s10, 0, 0x1c000
	s_add_i32 s11, s21, s39
	v_add_u32_e32 v143, s10, v167
	v_lshl_add_u64 v[164:165], v[164:165], 0, s[88:89]
	s_mov_b32 m0, s11
	ds_read_b128 v[208:211], v143
	ds_read_b128 v[212:215], v143 offset:1024
	ds_read_b128 v[216:219], v143 offset:2048
	ds_read_b128 v[220:223], v143 offset:3072
	global_load_lds_dwordx4 v[164:165], off
	v_lshl_add_u64 v[164:165], v[176:177], 0, s[88:89]
	s_add_i32 m0, s11, 0x2000
	s_nop 0
	global_load_lds_dwordx4 v[164:165], off
	s_barrier
	s_waitcnt lgkmcnt(0)
	s_setprio 1
	s_waitcnt lgkmcnt(0)
	v_mfma_f32_16x16x32_bf16 v[118:121], v[208:211], v[172:175], v[118:121]
	v_mfma_f32_16x16x32_bf16 v[114:117], v[216:219], v[172:175], v[114:117]
	v_mfma_f32_16x16x32_bf16 v[102:105], v[208:211], v[184:187], v[102:105]
	v_mfma_f32_16x16x32_bf16 v[98:101], v[216:219], v[184:187], v[98:101]
	v_mfma_f32_16x16x32_bf16 v[86:89], v[208:211], v[192:195], v[86:89]
	v_mfma_f32_16x16x32_bf16 v[82:85], v[216:219], v[192:195], v[82:85]
	v_mfma_f32_16x16x32_bf16 v[70:73], v[208:211], v[200:203], v[70:73]
	v_mfma_f32_16x16x32_bf16 v[66:69], v[216:219], v[200:203], v[66:69]
	v_mfma_f32_16x16x32_bf16 v[118:121], v[212:215], v[180:183], v[118:121]
	v_mfma_f32_16x16x32_bf16 v[114:117], v[220:223], v[180:183], v[114:117]
	v_mfma_f32_16x16x32_bf16 v[102:105], v[212:215], v[188:191], v[102:105]
	v_mfma_f32_16x16x32_bf16 v[98:101], v[220:223], v[188:191], v[98:101]
	v_mfma_f32_16x16x32_bf16 v[86:89], v[212:215], v[196:199], v[86:89]
	v_mfma_f32_16x16x32_bf16 v[82:85], v[220:223], v[196:199], v[82:85]
	v_mfma_f32_16x16x32_bf16 v[70:73], v[212:215], v[204:207], v[70:73]
	v_mfma_f32_16x16x32_bf16 v[66:69], v[220:223], v[204:207], v[66:69]
	s_setprio 0
	s_mov_b32 m0, s46
	v_lshl_add_u64 v[164:165], v[224:225], 0, s[88:89]
	s_barrier
	ds_read_b128 v[172:175], v171 offset:49152
	ds_read_b128 v[180:183], v171 offset:50176
	ds_read_b128 v[184:187], v171 offset:51200
	ds_read_b128 v[188:191], v171 offset:52224
	ds_read_b128 v[192:195], v171 offset:53248
	ds_read_b128 v[196:199], v171 offset:54272
	ds_read_b128 v[200:203], v171 offset:55296
	ds_read_b128 v[204:207], v171 offset:56320
	global_load_lds_dwordx4 v[164:165], off
	v_lshl_add_u64 v[164:165], v[236:237], 0, s[88:89]
	s_mov_b32 m0, s47
	s_nop 0
	global_load_lds_dwordx4 v[164:165], off
	s_barrier
	s_waitcnt lgkmcnt(0)
	s_setprio 1
	s_waitcnt lgkmcnt(0)
	v_mfma_f32_16x16x32_bf16 v[62:65], v[148:151], v[172:175], v[62:65]
	v_mfma_f32_16x16x32_bf16 v[58:61], v[156:159], v[172:175], v[58:61]
	v_mfma_f32_16x16x32_bf16 v[46:49], v[148:151], v[184:187], v[46:49]
	v_mfma_f32_16x16x32_bf16 v[42:45], v[156:159], v[184:187], v[42:45]
	v_mfma_f32_16x16x32_bf16 v[28:31], v[148:151], v[192:195], v[28:31]
	v_mfma_f32_16x16x32_bf16 v[24:27], v[156:159], v[192:195], v[24:27]
	v_mfma_f32_16x16x32_bf16 v[12:15], v[148:151], v[200:203], v[12:15]
	v_mfma_f32_16x16x32_bf16 v[8:11], v[156:159], v[200:203], v[8:11]
	v_mfma_f32_16x16x32_bf16 v[62:65], v[152:155], v[180:183], v[62:65]
	v_mfma_f32_16x16x32_bf16 v[58:61], v[160:163], v[180:183], v[58:61]
	v_mfma_f32_16x16x32_bf16 v[46:49], v[152:155], v[188:191], v[46:49]
	v_mfma_f32_16x16x32_bf16 v[42:45], v[160:163], v[188:191], v[42:45]
	v_mfma_f32_16x16x32_bf16 v[28:31], v[152:155], v[196:199], v[28:31]
	v_mfma_f32_16x16x32_bf16 v[24:27], v[160:163], v[196:199], v[24:27]
	v_mfma_f32_16x16x32_bf16 v[12:15], v[152:155], v[204:207], v[12:15]
	v_mfma_f32_16x16x32_bf16 v[8:11], v[160:163], v[204:207], v[8:11]
	s_setprio 0
	s_barrier
	s_add_u32 s8, s8, 0x80080
	s_addc_u32 s9, s9, 0
	s_add_i32 s10, s10, s39
	v_lshl_add_u64 v[148:149], s[8:9], 0, v[134:135]
	s_mov_b32 m0, s10
	s_nop 0
	global_load_lds_dwordx4 v[148:149], off
	v_lshl_add_u64 v[148:149], s[8:9], 0, v[130:131]
	s_add_i32 m0, s10, 0x2000
	s_nop 0
	global_load_lds_dwordx4 v[148:149], off
	s_waitcnt vmcnt(6)
	s_barrier
	s_setprio 1
	v_mfma_f32_16x16x32_bf16 v[54:57], v[208:211], v[172:175], v[54:57]
	v_mfma_f32_16x16x32_bf16 v[50:53], v[216:219], v[172:175], v[50:53]
	v_mfma_f32_16x16x32_bf16 v[38:41], v[208:211], v[184:187], v[38:41]
	v_mfma_f32_16x16x32_bf16 v[34:37], v[216:219], v[184:187], v[34:37]
	v_mfma_f32_16x16x32_bf16 v[20:23], v[208:211], v[192:195], v[20:23]
	v_mfma_f32_16x16x32_bf16 v[16:19], v[216:219], v[192:195], v[16:19]
	v_mfma_f32_16x16x32_bf16 v[4:7], v[208:211], v[200:203], v[4:7]
	v_mfma_f32_16x16x32_bf16 v[0:3], v[216:219], v[200:203], v[0:3]
	v_mfma_f32_16x16x32_bf16 v[54:57], v[212:215], v[180:183], v[54:57]
	v_mfma_f32_16x16x32_bf16 v[50:53], v[220:223], v[180:183], v[50:53]
	v_mfma_f32_16x16x32_bf16 v[38:41], v[212:215], v[188:191], v[38:41]
	v_mfma_f32_16x16x32_bf16 v[34:37], v[220:223], v[188:191], v[34:37]
	v_mfma_f32_16x16x32_bf16 v[20:23], v[212:215], v[196:199], v[20:23]
	v_mfma_f32_16x16x32_bf16 v[16:19], v[220:223], v[196:199], v[16:19]
	v_mfma_f32_16x16x32_bf16 v[4:7], v[212:215], v[204:207], v[4:7]
	v_mfma_f32_16x16x32_bf16 v[0:3], v[220:223], v[204:207], v[0:3]
	s_setprio 0
	s_add_i32 s20, s20, 2
	s_add_u32 s6, s6, 0x100
	s_addc_u32 s7, s7, 0
	s_add_u32 s13, s13, 0x100
	s_addc_u32 s15, s15, 0
	s_cmp_gt_u32 s20, 29
	s_barrier
	s_cbranch_scc0 .LBB0_372
	s_sub_i32 s6, s51, 8
	s_cmp_lt_u32 s6, 8
	s_cbranch_scc1 .Lmain_old
	s_sub_i32 s6, s51, 32
	s_cmp_lt_u32 s6, 12
	s_cbranch_scc1 .Lmain_kv
	v_mbcnt_lo_u32_b32 v217, -1, 0
	v_mbcnt_hi_u32_b32 v217, -1, v217
	v_lshrrev_b32_e32 v208, 4, v217
	v_bfe_u32 v209, v217, 2, 2
	v_and_b32_e32 v210, 3, v217
	v_lshl_add_u32 v216, v208, 2, v209
	v_lshl_add_u32 v217, v210, 4, v216
	v_lshlrev_b32_e32 v217, 2, v217
	v_add_u32_e32 v216, s45, v216
	v_lshlrev_b32_e32 v210, 4, v210
	s_lshl_b32 s6, s44, 6
	v_add_u32_e32 v210, s6, v210
	s_cmp_ge_u32 s51, 0x44
	s_cbranch_scc1 .Lmain_sig
	s_sub_i32 s6, s51, 44
	s_mov_b32 s7, 0x25e51000
	s_mov_b32 s13, 0x15e51000
	s_cmp_lt_i32 s6, 0
	s_cselect_b32 s6, s51, s6
	s_cselect_b32 s7, s13, s7
	s_lshr_b32 s13, s6, 3
	s_lshl_b32 s13, s13, 26
	s_add_i32 s7, s7, s13
	s_and_b32 s6, s6, 7
	s_lshl_b32 s6, s6, 9
	s_add_i32 s7, s7, s6
	s_lshl_b32 s6, s31, 20
	s_add_i32 s7, s7, s6
	s_add_u32 s22, s76, s7
	s_addc_u32 s23, s77, 0
	v_lshl_add_u32 v216, v216, 12, v210
	s_lshr_b32 s6, s51, 3
	s_cmp_eq_u32 s6, 3
	s_cbranch_scc1 .Lmain_q
	s_add_u32 s10, s22, 0
	s_addc_u32 s11, s23, 0
	v_cvt_pk_bf16_f32 v148, v126, v127
	v_cvt_pk_bf16_f32 v149, v128, v129
	v_cvt_pk_bf16_f32 v150, v122, v123
	v_cvt_pk_bf16_f32 v151, v124, v125
	ds_bpermute_b32 v180, v217, v148
	ds_bpermute_b32 v181, v217, v149
	ds_bpermute_b32 v182, v217, v150
	ds_bpermute_b32 v183, v217, v151
	v_cvt_pk_bf16_f32 v152, v118, v119
	v_cvt_pk_bf16_f32 v153, v120, v121
	v_cvt_pk_bf16_f32 v154, v114, v115
	v_cvt_pk_bf16_f32 v155, v116, v117
	ds_bpermute_b32 v184, v217, v152
	ds_bpermute_b32 v185, v217, v153
	ds_bpermute_b32 v186, v217, v154
	ds_bpermute_b32 v187, v217, v155
	s_add_u32 s20, s22, 0x10000
	s_addc_u32 s21, s23, 0
	v_cvt_pk_bf16_f32 v156, v110, v111
	v_cvt_pk_bf16_f32 v157, v112, v113
	v_cvt_pk_bf16_f32 v158, v106, v107
	v_cvt_pk_bf16_f32 v159, v108, v109
	ds_bpermute_b32 v188, v217, v156
	ds_bpermute_b32 v189, v217, v157
	ds_bpermute_b32 v190, v217, v158
	ds_bpermute_b32 v191, v217, v159
	v_cvt_pk_bf16_f32 v160, v102, v103
	v_cvt_pk_bf16_f32 v161, v104, v105
	v_cvt_pk_bf16_f32 v162, v98, v99
	v_cvt_pk_bf16_f32 v163, v100, v101
	ds_bpermute_b32 v192, v217, v160
	ds_bpermute_b32 v193, v217, v161
	ds_bpermute_b32 v194, v217, v162
	ds_bpermute_b32 v195, v217, v163
	s_waitcnt lgkmcnt(0)
	global_store_dwordx4 v216, v[180:183], s[10:11] nt
	global_store_dwordx4 v216, v[184:187], s[10:11] offset:256 nt
	global_store_dwordx4 v216, v[188:191], s[20:21] nt
	global_store_dwordx4 v216, v[192:195], s[20:21] offset:256 nt
	s_add_u32 s10, s22, 0x20000
	s_addc_u32 s11, s23, 0
	v_cvt_pk_bf16_f32 v148, v94, v95
	v_cvt_pk_bf16_f32 v149, v96, v97
	v_cvt_pk_bf16_f32 v150, v90, v91
	v_cvt_pk_bf16_f32 v151, v92, v93
	ds_bpermute_b32 v180, v217, v148
	ds_bpermute_b32 v181, v217, v149
	ds_bpermute_b32 v182, v217, v150
	ds_bpermute_b32 v183, v217, v151
	v_cvt_pk_bf16_f32 v152, v86, v87
	v_cvt_pk_bf16_f32 v153, v88, v89
	v_cvt_pk_bf16_f32 v154, v82, v83
	v_cvt_pk_bf16_f32 v155, v84, v85
	ds_bpermute_b32 v184, v217, v152
	ds_bpermute_b32 v185, v217, v153
	ds_bpermute_b32 v186, v217, v154
	ds_bpermute_b32 v187, v217, v155
	s_add_u32 s20, s22, 0x30000
	s_addc_u32 s21, s23, 0
	v_cvt_pk_bf16_f32 v156, v78, v79
	v_cvt_pk_bf16_f32 v157, v80, v81
	v_cvt_pk_bf16_f32 v158, v74, v75
	v_cvt_pk_bf16_f32 v159, v76, v77
	ds_bpermute_b32 v188, v217, v156
	ds_bpermute_b32 v189, v217, v157
	ds_bpermute_b32 v190, v217, v158
	ds_bpermute_b32 v191, v217, v159
	v_cvt_pk_bf16_f32 v160, v70, v71
	v_cvt_pk_bf16_f32 v161, v72, v73
	v_cvt_pk_bf16_f32 v162, v66, v67
	v_cvt_pk_bf16_f32 v163, v68, v69
	ds_bpermute_b32 v192, v217, v160
	ds_bpermute_b32 v193, v217, v161
	ds_bpermute_b32 v194, v217, v162
	ds_bpermute_b32 v195, v217, v163
	s_waitcnt lgkmcnt(0)
	global_store_dwordx4 v216, v[180:183], s[10:11] nt
	global_store_dwordx4 v216, v[184:187], s[10:11] offset:256 nt
	global_store_dwordx4 v216, v[188:191], s[20:21] nt
	global_store_dwordx4 v216, v[192:195], s[20:21] offset:256 nt
	s_add_u32 s10, s22, 0x80000
	s_addc_u32 s11, s23, 0
	v_cvt_pk_bf16_f32 v148, v62, v63
	v_cvt_pk_bf16_f32 v149, v64, v65
	v_cvt_pk_bf16_f32 v150, v58, v59
	v_cvt_pk_bf16_f32 v151, v60, v61
	ds_bpermute_b32 v180, v217, v148
	ds_bpermute_b32 v181, v217, v149
	ds_bpermute_b32 v182, v217, v150
	ds_bpermute_b32 v183, v217, v151
	v_cvt_pk_bf16_f32 v152, v54, v55
	v_cvt_pk_bf16_f32 v153, v56, v57
	v_cvt_pk_bf16_f32 v154, v50, v51
	v_cvt_pk_bf16_f32 v155, v52, v53
	ds_bpermute_b32 v184, v217, v152
	ds_bpermute_b32 v185, v217, v153
	ds_bpermute_b32 v186, v217, v154
	ds_bpermute_b32 v187, v217, v155
	s_add_u32 s20, s22, 0x90000
	s_addc_u32 s21, s23, 0
	v_cvt_pk_bf16_f32 v156, v46, v47
	v_cvt_pk_bf16_f32 v157, v48, v49
	v_cvt_pk_bf16_f32 v158, v42, v43
	v_cvt_pk_bf16_f32 v159, v44, v45
	ds_bpermute_b32 v188, v217, v156
	ds_bpermute_b32 v189, v217, v157
	ds_bpermute_b32 v190, v217, v158
	ds_bpermute_b32 v191, v217, v159
	v_cvt_pk_bf16_f32 v160, v38, v39
	v_cvt_pk_bf16_f32 v161, v40, v41
	v_cvt_pk_bf16_f32 v162, v34, v35
	v_cvt_pk_bf16_f32 v163, v36, v37
	ds_bpermute_b32 v192, v217, v160
	ds_bpermute_b32 v193, v217, v161
	ds_bpermute_b32 v194, v217, v162
	ds_bpermute_b32 v195, v217, v163
	s_waitcnt lgkmcnt(0)
	global_store_dwordx4 v216, v[180:183], s[10:11] nt
	global_store_dwordx4 v216, v[184:187], s[10:11] offset:256 nt
	global_store_dwordx4 v216, v[188:191], s[20:21] nt
	global_store_dwordx4 v216, v[192:195], s[20:21] offset:256 nt
	s_add_u32 s10, s22, 0xa0000
	s_addc_u32 s11, s23, 0
	v_cvt_pk_bf16_f32 v148, v28, v29
	v_cvt_pk_bf16_f32 v149, v30, v31
	v_cvt_pk_bf16_f32 v150, v24, v25
	v_cvt_pk_bf16_f32 v151, v26, v27
	ds_bpermute_b32 v180, v217, v148
	ds_bpermute_b32 v181, v217, v149
	ds_bpermute_b32 v182, v217, v150
	ds_bpermute_b32 v183, v217, v151
	v_cvt_pk_bf16_f32 v152, v20, v21
	v_cvt_pk_bf16_f32 v153, v22, v23
	v_cvt_pk_bf16_f32 v154, v16, v17
	v_cvt_pk_bf16_f32 v155, v18, v19
	ds_bpermute_b32 v184, v217, v152
	ds_bpermute_b32 v185, v217, v153
	ds_bpermute_b32 v186, v217, v154
	ds_bpermute_b32 v187, v217, v155
	s_add_u32 s20, s22, 0xb0000
	s_addc_u32 s21, s23, 0
	v_cvt_pk_bf16_f32 v156, v12, v13
	v_cvt_pk_bf16_f32 v157, v14, v15
	v_cvt_pk_bf16_f32 v158, v8, v9
	v_cvt_pk_bf16_f32 v159, v10, v11
	ds_bpermute_b32 v188, v217, v156
	ds_bpermute_b32 v189, v217, v157
	ds_bpermute_b32 v190, v217, v158
	ds_bpermute_b32 v191, v217, v159
	v_cvt_pk_bf16_f32 v160, v4, v5
	v_cvt_pk_bf16_f32 v161, v6, v7
	v_cvt_pk_bf16_f32 v162, v0, v1
	v_cvt_pk_bf16_f32 v163, v2, v3
	ds_bpermute_b32 v192, v217, v160
	ds_bpermute_b32 v193, v217, v161
	ds_bpermute_b32 v194, v217, v162
	ds_bpermute_b32 v195, v217, v163
	s_waitcnt lgkmcnt(0)
	global_store_dwordx4 v216, v[180:183], s[10:11] nt
	global_store_dwordx4 v216, v[184:187], s[10:11] offset:256 nt
	global_store_dwordx4 v216, v[188:191], s[20:21] nt
	global_store_dwordx4 v216, v[192:195], s[20:21] offset:256 nt
	s_branch .LBB0_364
.Lmain_q:
	s_mov_b32 s6, 0x3e0293ee
	s_add_u32 s10, s22, 0
	s_addc_u32 s11, s23, 0
	v_pk_mul_f32 v[126:127], v[126:127], s[6:7] op_sel_hi:[1,0]
	v_pk_mul_f32 v[128:129], v[128:129], s[6:7] op_sel_hi:[1,0]
	v_pk_mul_f32 v[122:123], v[122:123], s[6:7] op_sel_hi:[1,0]
	v_pk_mul_f32 v[124:125], v[124:125], s[6:7] op_sel_hi:[1,0]
	v_cvt_pk_bf16_f32 v148, v126, v127
	v_cvt_pk_bf16_f32 v149, v128, v129
	v_cvt_pk_bf16_f32 v150, v122, v123
	v_cvt_pk_bf16_f32 v151, v124, v125
	ds_bpermute_b32 v180, v217, v148
	ds_bpermute_b32 v181, v217, v149
	ds_bpermute_b32 v182, v217, v150
	ds_bpermute_b32 v183, v217, v151
	v_pk_mul_f32 v[118:119], v[118:119], s[6:7] op_sel_hi:[1,0]
	v_pk_mul_f32 v[120:121], v[120:121], s[6:7] op_sel_hi:[1,0]
	v_pk_mul_f32 v[114:115], v[114:115], s[6:7] op_sel_hi:[1,0]
	v_pk_mul_f32 v[116:117], v[116:117], s[6:7] op_sel_hi:[1,0]
	v_cvt_pk_bf16_f32 v152, v118, v119
	v_cvt_pk_bf16_f32 v153, v120, v121
	v_cvt_pk_bf16_f32 v154, v114, v115
	v_cvt_pk_bf16_f32 v155, v116, v117
	ds_bpermute_b32 v184, v217, v152
	ds_bpermute_b32 v185, v217, v153
	ds_bpermute_b32 v186, v217, v154
	ds_bpermute_b32 v187, v217, v155
	s_add_u32 s20, s22, 0x10000
	s_addc_u32 s21, s23, 0
	v_pk_mul_f32 v[110:111], v[110:111], s[6:7] op_sel_hi:[1,0]
	v_pk_mul_f32 v[112:113], v[112:113], s[6:7] op_sel_hi:[1,0]
	v_pk_mul_f32 v[106:107], v[106:107], s[6:7] op_sel_hi:[1,0]
	v_pk_mul_f32 v[108:109], v[108:109], s[6:7] op_sel_hi:[1,0]
	v_cvt_pk_bf16_f32 v156, v110, v111
	v_cvt_pk_bf16_f32 v157, v112, v113
	v_cvt_pk_bf16_f32 v158, v106, v107
	v_cvt_pk_bf16_f32 v159, v108, v109
	ds_bpermute_b32 v188, v217, v156
	ds_bpermute_b32 v189, v217, v157
	ds_bpermute_b32 v190, v217, v158
	ds_bpermute_b32 v191, v217, v159
	v_pk_mul_f32 v[102:103], v[102:103], s[6:7] op_sel_hi:[1,0]
	v_pk_mul_f32 v[104:105], v[104:105], s[6:7] op_sel_hi:[1,0]
	v_pk_mul_f32 v[98:99], v[98:99], s[6:7] op_sel_hi:[1,0]
	v_pk_mul_f32 v[100:101], v[100:101], s[6:7] op_sel_hi:[1,0]
	v_cvt_pk_bf16_f32 v160, v102, v103
	v_cvt_pk_bf16_f32 v161, v104, v105
	v_cvt_pk_bf16_f32 v162, v98, v99
	v_cvt_pk_bf16_f32 v163, v100, v101
	ds_bpermute_b32 v192, v217, v160
	ds_bpermute_b32 v193, v217, v161
	ds_bpermute_b32 v194, v217, v162
	ds_bpermute_b32 v195, v217, v163
	s_waitcnt lgkmcnt(0)
	global_store_dwordx4 v216, v[180:183], s[10:11] nt
	global_store_dwordx4 v216, v[184:187], s[10:11] offset:256 nt
	global_store_dwordx4 v216, v[188:191], s[20:21] nt
	global_store_dwordx4 v216, v[192:195], s[20:21] offset:256 nt
	s_add_u32 s10, s22, 0x20000
	s_addc_u32 s11, s23, 0
	v_pk_mul_f32 v[94:95], v[94:95], s[6:7] op_sel_hi:[1,0]
	v_pk_mul_f32 v[96:97], v[96:97], s[6:7] op_sel_hi:[1,0]
	v_pk_mul_f32 v[90:91], v[90:91], s[6:7] op_sel_hi:[1,0]
	v_pk_mul_f32 v[92:93], v[92:93], s[6:7] op_sel_hi:[1,0]
	v_cvt_pk_bf16_f32 v148, v94, v95
	v_cvt_pk_bf16_f32 v149, v96, v97
	v_cvt_pk_bf16_f32 v150, v90, v91
	v_cvt_pk_bf16_f32 v151, v92, v93
	ds_bpermute_b32 v180, v217, v148
	ds_bpermute_b32 v181, v217, v149
	ds_bpermute_b32 v182, v217, v150
	ds_bpermute_b32 v183, v217, v151
	v_pk_mul_f32 v[86:87], v[86:87], s[6:7] op_sel_hi:[1,0]
	v_pk_mul_f32 v[88:89], v[88:89], s[6:7] op_sel_hi:[1,0]
	v_pk_mul_f32 v[82:83], v[82:83], s[6:7] op_sel_hi:[1,0]
	v_pk_mul_f32 v[84:85], v[84:85], s[6:7] op_sel_hi:[1,0]
	v_cvt_pk_bf16_f32 v152, v86, v87
	v_cvt_pk_bf16_f32 v153, v88, v89
	v_cvt_pk_bf16_f32 v154, v82, v83
	v_cvt_pk_bf16_f32 v155, v84, v85
	ds_bpermute_b32 v184, v217, v152
	ds_bpermute_b32 v185, v217, v153
	ds_bpermute_b32 v186, v217, v154
	ds_bpermute_b32 v187, v217, v155
	s_add_u32 s20, s22, 0x30000
	s_addc_u32 s21, s23, 0
	v_pk_mul_f32 v[78:79], v[78:79], s[6:7] op_sel_hi:[1,0]
	v_pk_mul_f32 v[80:81], v[80:81], s[6:7] op_sel_hi:[1,0]
	v_pk_mul_f32 v[74:75], v[74:75], s[6:7] op_sel_hi:[1,0]
	v_pk_mul_f32 v[76:77], v[76:77], s[6:7] op_sel_hi:[1,0]
	v_cvt_pk_bf16_f32 v156, v78, v79
	v_cvt_pk_bf16_f32 v157, v80, v81
	v_cvt_pk_bf16_f32 v158, v74, v75
	v_cvt_pk_bf16_f32 v159, v76, v77
	ds_bpermute_b32 v188, v217, v156
	ds_bpermute_b32 v189, v217, v157
	ds_bpermute_b32 v190, v217, v158
	ds_bpermute_b32 v191, v217, v159
	v_pk_mul_f32 v[70:71], v[70:71], s[6:7] op_sel_hi:[1,0]
	v_pk_mul_f32 v[72:73], v[72:73], s[6:7] op_sel_hi:[1,0]
	v_pk_mul_f32 v[66:67], v[66:67], s[6:7] op_sel_hi:[1,0]
	v_pk_mul_f32 v[68:69], v[68:69], s[6:7] op_sel_hi:[1,0]
	v_cvt_pk_bf16_f32 v160, v70, v71
	v_cvt_pk_bf16_f32 v161, v72, v73
	v_cvt_pk_bf16_f32 v162, v66, v67
	v_cvt_pk_bf16_f32 v163, v68, v69
	ds_bpermute_b32 v192, v217, v160
	ds_bpermute_b32 v193, v217, v161
	ds_bpermute_b32 v194, v217, v162
	ds_bpermute_b32 v195, v217, v163
	s_waitcnt lgkmcnt(0)
	global_store_dwordx4 v216, v[180:183], s[10:11] nt
	global_store_dwordx4 v216, v[184:187], s[10:11] offset:256 nt
	global_store_dwordx4 v216, v[188:191], s[20:21] nt
	global_store_dwordx4 v216, v[192:195], s[20:21] offset:256 nt
	s_add_u32 s10, s22, 0x80000
	s_addc_u32 s11, s23, 0
	v_pk_mul_f32 v[62:63], v[62:63], s[6:7] op_sel_hi:[1,0]
	v_pk_mul_f32 v[64:65], v[64:65], s[6:7] op_sel_hi:[1,0]
	v_pk_mul_f32 v[58:59], v[58:59], s[6:7] op_sel_hi:[1,0]
	v_pk_mul_f32 v[60:61], v[60:61], s[6:7] op_sel_hi:[1,0]
	v_cvt_pk_bf16_f32 v148, v62, v63
	v_cvt_pk_bf16_f32 v149, v64, v65
	v_cvt_pk_bf16_f32 v150, v58, v59
	v_cvt_pk_bf16_f32 v151, v60, v61
	ds_bpermute_b32 v180, v217, v148
	ds_bpermute_b32 v181, v217, v149
	ds_bpermute_b32 v182, v217, v150
	ds_bpermute_b32 v183, v217, v151
	v_pk_mul_f32 v[54:55], v[54:55], s[6:7] op_sel_hi:[1,0]
	v_pk_mul_f32 v[56:57], v[56:57], s[6:7] op_sel_hi:[1,0]
	v_pk_mul_f32 v[50:51], v[50:51], s[6:7] op_sel_hi:[1,0]
	v_pk_mul_f32 v[52:53], v[52:53], s[6:7] op_sel_hi:[1,0]
	v_cvt_pk_bf16_f32 v152, v54, v55
	v_cvt_pk_bf16_f32 v153, v56, v57
	v_cvt_pk_bf16_f32 v154, v50, v51
	v_cvt_pk_bf16_f32 v155, v52, v53
	ds_bpermute_b32 v184, v217, v152
	ds_bpermute_b32 v185, v217, v153
	ds_bpermute_b32 v186, v217, v154
	ds_bpermute_b32 v187, v217, v155
	s_add_u32 s20, s22, 0x90000
	s_addc_u32 s21, s23, 0
	v_pk_mul_f32 v[46:47], v[46:47], s[6:7] op_sel_hi:[1,0]
	v_pk_mul_f32 v[48:49], v[48:49], s[6:7] op_sel_hi:[1,0]
	v_pk_mul_f32 v[42:43], v[42:43], s[6:7] op_sel_hi:[1,0]
	v_pk_mul_f32 v[44:45], v[44:45], s[6:7] op_sel_hi:[1,0]
	v_cvt_pk_bf16_f32 v156, v46, v47
	v_cvt_pk_bf16_f32 v157, v48, v49
	v_cvt_pk_bf16_f32 v158, v42, v43
	v_cvt_pk_bf16_f32 v159, v44, v45
	ds_bpermute_b32 v188, v217, v156
	ds_bpermute_b32 v189, v217, v157
	ds_bpermute_b32 v190, v217, v158
	ds_bpermute_b32 v191, v217, v159
	v_pk_mul_f32 v[38:39], v[38:39], s[6:7] op_sel_hi:[1,0]
	v_pk_mul_f32 v[40:41], v[40:41], s[6:7] op_sel_hi:[1,0]
	v_pk_mul_f32 v[34:35], v[34:35], s[6:7] op_sel_hi:[1,0]
	v_pk_mul_f32 v[36:37], v[36:37], s[6:7] op_sel_hi:[1,0]
	v_cvt_pk_bf16_f32 v160, v38, v39
	v_cvt_pk_bf16_f32 v161, v40, v41
	v_cvt_pk_bf16_f32 v162, v34, v35
	v_cvt_pk_bf16_f32 v163, v36, v37
	ds_bpermute_b32 v192, v217, v160
	ds_bpermute_b32 v193, v217, v161
	ds_bpermute_b32 v194, v217, v162
	ds_bpermute_b32 v195, v217, v163
	s_waitcnt lgkmcnt(0)
	global_store_dwordx4 v216, v[180:183], s[10:11] nt
	global_store_dwordx4 v216, v[184:187], s[10:11] offset:256 nt
	global_store_dwordx4 v216, v[188:191], s[20:21] nt
	global_store_dwordx4 v216, v[192:195], s[20:21] offset:256 nt
	s_add_u32 s10, s22, 0xa0000
	s_addc_u32 s11, s23, 0
	v_pk_mul_f32 v[28:29], v[28:29], s[6:7] op_sel_hi:[1,0]
	v_pk_mul_f32 v[30:31], v[30:31], s[6:7] op_sel_hi:[1,0]
	v_pk_mul_f32 v[24:25], v[24:25], s[6:7] op_sel_hi:[1,0]
	v_pk_mul_f32 v[26:27], v[26:27], s[6:7] op_sel_hi:[1,0]
	v_cvt_pk_bf16_f32 v148, v28, v29
	v_cvt_pk_bf16_f32 v149, v30, v31
	v_cvt_pk_bf16_f32 v150, v24, v25
	v_cvt_pk_bf16_f32 v151, v26, v27
	ds_bpermute_b32 v180, v217, v148
	ds_bpermute_b32 v181, v217, v149
	ds_bpermute_b32 v182, v217, v150
	ds_bpermute_b32 v183, v217, v151
	v_pk_mul_f32 v[20:21], v[20:21], s[6:7] op_sel_hi:[1,0]
	v_pk_mul_f32 v[22:23], v[22:23], s[6:7] op_sel_hi:[1,0]
	v_pk_mul_f32 v[16:17], v[16:17], s[6:7] op_sel_hi:[1,0]
	v_pk_mul_f32 v[18:19], v[18:19], s[6:7] op_sel_hi:[1,0]
	v_cvt_pk_bf16_f32 v152, v20, v21
	v_cvt_pk_bf16_f32 v153, v22, v23
	v_cvt_pk_bf16_f32 v154, v16, v17
	v_cvt_pk_bf16_f32 v155, v18, v19
	ds_bpermute_b32 v184, v217, v152
	ds_bpermute_b32 v185, v217, v153
	ds_bpermute_b32 v186, v217, v154
	ds_bpermute_b32 v187, v217, v155
	s_add_u32 s20, s22, 0xb0000
	s_addc_u32 s21, s23, 0
	v_pk_mul_f32 v[12:13], v[12:13], s[6:7] op_sel_hi:[1,0]
	v_pk_mul_f32 v[14:15], v[14:15], s[6:7] op_sel_hi:[1,0]
	v_pk_mul_f32 v[8:9], v[8:9], s[6:7] op_sel_hi:[1,0]
	v_pk_mul_f32 v[10:11], v[10:11], s[6:7] op_sel_hi:[1,0]
	v_cvt_pk_bf16_f32 v156, v12, v13
	v_cvt_pk_bf16_f32 v157, v14, v15
	v_cvt_pk_bf16_f32 v158, v8, v9
	v_cvt_pk_bf16_f32 v159, v10, v11
	ds_bpermute_b32 v188, v217, v156
	ds_bpermute_b32 v189, v217, v157
	ds_bpermute_b32 v190, v217, v158
	ds_bpermute_b32 v191, v217, v159
	v_pk_mul_f32 v[4:5], v[4:5], s[6:7] op_sel_hi:[1,0]
	v_pk_mul_f32 v[6:7], v[6:7], s[6:7] op_sel_hi:[1,0]
	v_pk_mul_f32 v[0:1], v[0:1], s[6:7] op_sel_hi:[1,0]
	v_pk_mul_f32 v[2:3], v[2:3], s[6:7] op_sel_hi:[1,0]
	v_cvt_pk_bf16_f32 v160, v4, v5
	v_cvt_pk_bf16_f32 v161, v6, v7
	v_cvt_pk_bf16_f32 v162, v0, v1
	v_cvt_pk_bf16_f32 v163, v2, v3
	ds_bpermute_b32 v192, v217, v160
	ds_bpermute_b32 v193, v217, v161
	ds_bpermute_b32 v194, v217, v162
	ds_bpermute_b32 v195, v217, v163
	s_waitcnt lgkmcnt(0)
	global_store_dwordx4 v216, v[180:183], s[10:11] nt
	global_store_dwordx4 v216, v[184:187], s[10:11] offset:256 nt
	global_store_dwordx4 v216, v[188:191], s[20:21] nt
	global_store_dwordx4 v216, v[192:195], s[20:21] offset:256 nt
	s_branch .LBB0_364
.Lmain_sig:
	s_mul_i32 s7, s31, 0x300000
	s_sub_i32 s6, s51, 0x44
	s_lshl_b32 s6, s6, 9
	s_add_i32 s7, s7, s6
	s_add_i32 s7, s7, 0x37f51000
	s_add_u32 s22, s76, s7
	s_addc_u32 s23, s77, 0
	v_mul_u32_u24_e32 v216, 0x3000, v216
	v_add_u32_e32 v216, v216, v210
	s_add_u32 s10, s22, 0
	s_addc_u32 s11, s23, 0
	v_mul_f32_e32 v208, 0xbfb8aa3b, v126
	v_mul_f32_e32 v209, 0xbfb8aa3b, v127
	v_mul_f32_e32 v210, 0xbfb8aa3b, v128
	v_mul_f32_e32 v211, 0xbfb8aa3b, v129
	v_mul_f32_e32 v212, 0xbfb8aa3b, v122
	v_mul_f32_e32 v213, 0xbfb8aa3b, v123
	v_mul_f32_e32 v214, 0xbfb8aa3b, v124
	v_mul_f32_e32 v215, 0xbfb8aa3b, v125
	v_exp_f32_e32 v208, v208
	v_exp_f32_e32 v209, v209
	v_exp_f32_e32 v210, v210
	v_exp_f32_e32 v211, v211
	v_exp_f32_e32 v212, v212
	v_exp_f32_e32 v213, v213
	v_exp_f32_e32 v214, v214
	v_exp_f32_e32 v215, v215
	v_add_f32_e32 v208, 1.0, v208
	v_add_f32_e32 v209, 1.0, v209
	v_add_f32_e32 v210, 1.0, v210
	v_add_f32_e32 v211, 1.0, v211
	v_add_f32_e32 v212, 1.0, v212
	v_add_f32_e32 v213, 1.0, v213
	v_add_f32_e32 v214, 1.0, v214
	v_add_f32_e32 v215, 1.0, v215
	v_rcp_f32_e32 v208, v208
	v_rcp_f32_e32 v209, v209
	v_rcp_f32_e32 v210, v210
	v_rcp_f32_e32 v211, v211
	v_rcp_f32_e32 v212, v212
	v_rcp_f32_e32 v213, v213
	v_rcp_f32_e32 v214, v214
	v_rcp_f32_e32 v215, v215
	v_cvt_pk_bf16_f32 v148, v208, v209
	v_cvt_pk_bf16_f32 v149, v210, v211
	v_cvt_pk_bf16_f32 v150, v212, v213
	v_cvt_pk_bf16_f32 v151, v214, v215
	ds_bpermute_b32 v180, v217, v148
	ds_bpermute_b32 v181, v217, v149
	ds_bpermute_b32 v182, v217, v150
	ds_bpermute_b32 v183, v217, v151
	v_mul_f32_e32 v208, 0xbfb8aa3b, v118
	v_mul_f32_e32 v209, 0xbfb8aa3b, v119
	v_mul_f32_e32 v210, 0xbfb8aa3b, v120
	v_mul_f32_e32 v211, 0xbfb8aa3b, v121
	v_mul_f32_e32 v212, 0xbfb8aa3b, v114
	v_mul_f32_e32 v213, 0xbfb8aa3b, v115
	v_mul_f32_e32 v214, 0xbfb8aa3b, v116
	v_mul_f32_e32 v215, 0xbfb8aa3b, v117
	v_exp_f32_e32 v208, v208
	v_exp_f32_e32 v209, v209
	v_exp_f32_e32 v210, v210
	v_exp_f32_e32 v211, v211
	v_exp_f32_e32 v212, v212
	v_exp_f32_e32 v213, v213
	v_exp_f32_e32 v214, v214
	v_exp_f32_e32 v215, v215
	v_add_f32_e32 v208, 1.0, v208
	v_add_f32_e32 v209, 1.0, v209
	v_add_f32_e32 v210, 1.0, v210
	v_add_f32_e32 v211, 1.0, v211
	v_add_f32_e32 v212, 1.0, v212
	v_add_f32_e32 v213, 1.0, v213
	v_add_f32_e32 v214, 1.0, v214
	v_add_f32_e32 v215, 1.0, v215
	v_rcp_f32_e32 v208, v208
	v_rcp_f32_e32 v209, v209
	v_rcp_f32_e32 v210, v210
	v_rcp_f32_e32 v211, v211
	v_rcp_f32_e32 v212, v212
	v_rcp_f32_e32 v213, v213
	v_rcp_f32_e32 v214, v214
	v_rcp_f32_e32 v215, v215
	v_cvt_pk_bf16_f32 v152, v208, v209
	v_cvt_pk_bf16_f32 v153, v210, v211
	v_cvt_pk_bf16_f32 v154, v212, v213
	v_cvt_pk_bf16_f32 v155, v214, v215
	ds_bpermute_b32 v184, v217, v152
	ds_bpermute_b32 v185, v217, v153
	ds_bpermute_b32 v186, v217, v154
	ds_bpermute_b32 v187, v217, v155
	s_add_u32 s20, s22, 0x30000
	s_addc_u32 s21, s23, 0
	v_mul_f32_e32 v208, 0xbfb8aa3b, v110
	v_mul_f32_e32 v209, 0xbfb8aa3b, v111
	v_mul_f32_e32 v210, 0xbfb8aa3b, v112
	v_mul_f32_e32 v211, 0xbfb8aa3b, v113
	v_mul_f32_e32 v212, 0xbfb8aa3b, v106
	v_mul_f32_e32 v213, 0xbfb8aa3b, v107
	v_mul_f32_e32 v214, 0xbfb8aa3b, v108
	v_mul_f32_e32 v215, 0xbfb8aa3b, v109
	v_exp_f32_e32 v208, v208
	v_exp_f32_e32 v209, v209
	v_exp_f32_e32 v210, v210
	v_exp_f32_e32 v211, v211
	v_exp_f32_e32 v212, v212
	v_exp_f32_e32 v213, v213
	v_exp_f32_e32 v214, v214
	v_exp_f32_e32 v215, v215
	v_add_f32_e32 v208, 1.0, v208
	v_add_f32_e32 v209, 1.0, v209
	v_add_f32_e32 v210, 1.0, v210
	v_add_f32_e32 v211, 1.0, v211
	v_add_f32_e32 v212, 1.0, v212
	v_add_f32_e32 v213, 1.0, v213
	v_add_f32_e32 v214, 1.0, v214
	v_add_f32_e32 v215, 1.0, v215
	v_rcp_f32_e32 v208, v208
	v_rcp_f32_e32 v209, v209
	v_rcp_f32_e32 v210, v210
	v_rcp_f32_e32 v211, v211
	v_rcp_f32_e32 v212, v212
	v_rcp_f32_e32 v213, v213
	v_rcp_f32_e32 v214, v214
	v_rcp_f32_e32 v215, v215
	v_cvt_pk_bf16_f32 v156, v208, v209
	v_cvt_pk_bf16_f32 v157, v210, v211
	v_cvt_pk_bf16_f32 v158, v212, v213
	v_cvt_pk_bf16_f32 v159, v214, v215
	ds_bpermute_b32 v188, v217, v156
	ds_bpermute_b32 v189, v217, v157
	ds_bpermute_b32 v190, v217, v158
	ds_bpermute_b32 v191, v217, v159
	v_mul_f32_e32 v208, 0xbfb8aa3b, v102
	v_mul_f32_e32 v209, 0xbfb8aa3b, v103
	v_mul_f32_e32 v210, 0xbfb8aa3b, v104
	v_mul_f32_e32 v211, 0xbfb8aa3b, v105
	v_mul_f32_e32 v212, 0xbfb8aa3b, v98
	v_mul_f32_e32 v213, 0xbfb8aa3b, v99
	v_mul_f32_e32 v214, 0xbfb8aa3b, v100
	v_mul_f32_e32 v215, 0xbfb8aa3b, v101
	v_exp_f32_e32 v208, v208
	v_exp_f32_e32 v209, v209
	v_exp_f32_e32 v210, v210
	v_exp_f32_e32 v211, v211
	v_exp_f32_e32 v212, v212
	v_exp_f32_e32 v213, v213
	v_exp_f32_e32 v214, v214
	v_exp_f32_e32 v215, v215
	v_add_f32_e32 v208, 1.0, v208
	v_add_f32_e32 v209, 1.0, v209
	v_add_f32_e32 v210, 1.0, v210
	v_add_f32_e32 v211, 1.0, v211
	v_add_f32_e32 v212, 1.0, v212
	v_add_f32_e32 v213, 1.0, v213
	v_add_f32_e32 v214, 1.0, v214
	v_add_f32_e32 v215, 1.0, v215
	v_rcp_f32_e32 v208, v208
	v_rcp_f32_e32 v209, v209
	v_rcp_f32_e32 v210, v210
	v_rcp_f32_e32 v211, v211
	v_rcp_f32_e32 v212, v212
	v_rcp_f32_e32 v213, v213
	v_rcp_f32_e32 v214, v214
	v_rcp_f32_e32 v215, v215
	v_cvt_pk_bf16_f32 v160, v208, v209
	v_cvt_pk_bf16_f32 v161, v210, v211
	v_cvt_pk_bf16_f32 v162, v212, v213
	v_cvt_pk_bf16_f32 v163, v214, v215
	ds_bpermute_b32 v192, v217, v160
	ds_bpermute_b32 v193, v217, v161
	ds_bpermute_b32 v194, v217, v162
	ds_bpermute_b32 v195, v217, v163
	s_waitcnt lgkmcnt(0)
	global_store_dwordx4 v216, v[180:183], s[10:11] nt
	global_store_dwordx4 v216, v[184:187], s[10:11] offset:256 nt
	global_store_dwordx4 v216, v[188:191], s[20:21] nt
	global_store_dwordx4 v216, v[192:195], s[20:21] offset:256 nt
	s_add_u32 s10, s22, 0x60000
	s_addc_u32 s11, s23, 0
	v_mul_f32_e32 v208, 0xbfb8aa3b, v94
	v_mul_f32_e32 v209, 0xbfb8aa3b, v95
	v_mul_f32_e32 v210, 0xbfb8aa3b, v96
	v_mul_f32_e32 v211, 0xbfb8aa3b, v97
	v_mul_f32_e32 v212, 0xbfb8aa3b, v90
	v_mul_f32_e32 v213, 0xbfb8aa3b, v91
	v_mul_f32_e32 v214, 0xbfb8aa3b, v92
	v_mul_f32_e32 v215, 0xbfb8aa3b, v93
	v_exp_f32_e32 v208, v208
	v_exp_f32_e32 v209, v209
	v_exp_f32_e32 v210, v210
	v_exp_f32_e32 v211, v211
	v_exp_f32_e32 v212, v212
	v_exp_f32_e32 v213, v213
	v_exp_f32_e32 v214, v214
	v_exp_f32_e32 v215, v215
	v_add_f32_e32 v208, 1.0, v208
	v_add_f32_e32 v209, 1.0, v209
	v_add_f32_e32 v210, 1.0, v210
	v_add_f32_e32 v211, 1.0, v211
	v_add_f32_e32 v212, 1.0, v212
	v_add_f32_e32 v213, 1.0, v213
	v_add_f32_e32 v214, 1.0, v214
	v_add_f32_e32 v215, 1.0, v215
	v_rcp_f32_e32 v208, v208
	v_rcp_f32_e32 v209, v209
	v_rcp_f32_e32 v210, v210
	v_rcp_f32_e32 v211, v211
	v_rcp_f32_e32 v212, v212
	v_rcp_f32_e32 v213, v213
	v_rcp_f32_e32 v214, v214
	v_rcp_f32_e32 v215, v215
	v_cvt_pk_bf16_f32 v148, v208, v209
	v_cvt_pk_bf16_f32 v149, v210, v211
	v_cvt_pk_bf16_f32 v150, v212, v213
	v_cvt_pk_bf16_f32 v151, v214, v215
	ds_bpermute_b32 v180, v217, v148
	ds_bpermute_b32 v181, v217, v149
	ds_bpermute_b32 v182, v217, v150
	ds_bpermute_b32 v183, v217, v151
	v_mul_f32_e32 v208, 0xbfb8aa3b, v86
	v_mul_f32_e32 v209, 0xbfb8aa3b, v87
	v_mul_f32_e32 v210, 0xbfb8aa3b, v88
	v_mul_f32_e32 v211, 0xbfb8aa3b, v89
	v_mul_f32_e32 v212, 0xbfb8aa3b, v82
	v_mul_f32_e32 v213, 0xbfb8aa3b, v83
	v_mul_f32_e32 v214, 0xbfb8aa3b, v84
	v_mul_f32_e32 v215, 0xbfb8aa3b, v85
	v_exp_f32_e32 v208, v208
	v_exp_f32_e32 v209, v209
	v_exp_f32_e32 v210, v210
	v_exp_f32_e32 v211, v211
	v_exp_f32_e32 v212, v212
	v_exp_f32_e32 v213, v213
	v_exp_f32_e32 v214, v214
	v_exp_f32_e32 v215, v215
	v_add_f32_e32 v208, 1.0, v208
	v_add_f32_e32 v209, 1.0, v209
	v_add_f32_e32 v210, 1.0, v210
	v_add_f32_e32 v211, 1.0, v211
	v_add_f32_e32 v212, 1.0, v212
	v_add_f32_e32 v213, 1.0, v213
	v_add_f32_e32 v214, 1.0, v214
	v_add_f32_e32 v215, 1.0, v215
	v_rcp_f32_e32 v208, v208
	v_rcp_f32_e32 v209, v209
	v_rcp_f32_e32 v210, v210
	v_rcp_f32_e32 v211, v211
	v_rcp_f32_e32 v212, v212
	v_rcp_f32_e32 v213, v213
	v_rcp_f32_e32 v214, v214
	v_rcp_f32_e32 v215, v215
	v_cvt_pk_bf16_f32 v152, v208, v209
	v_cvt_pk_bf16_f32 v153, v210, v211
	v_cvt_pk_bf16_f32 v154, v212, v213
	v_cvt_pk_bf16_f32 v155, v214, v215
	ds_bpermute_b32 v184, v217, v152
	ds_bpermute_b32 v185, v217, v153
	ds_bpermute_b32 v186, v217, v154
	ds_bpermute_b32 v187, v217, v155
	s_add_u32 s20, s22, 0x90000
	s_addc_u32 s21, s23, 0
	v_mul_f32_e32 v208, 0xbfb8aa3b, v78
	v_mul_f32_e32 v209, 0xbfb8aa3b, v79
	v_mul_f32_e32 v210, 0xbfb8aa3b, v80
	v_mul_f32_e32 v211, 0xbfb8aa3b, v81
	v_mul_f32_e32 v212, 0xbfb8aa3b, v74
	v_mul_f32_e32 v213, 0xbfb8aa3b, v75
	v_mul_f32_e32 v214, 0xbfb8aa3b, v76
	v_mul_f32_e32 v215, 0xbfb8aa3b, v77
	v_exp_f32_e32 v208, v208
	v_exp_f32_e32 v209, v209
	v_exp_f32_e32 v210, v210
	v_exp_f32_e32 v211, v211
	v_exp_f32_e32 v212, v212
	v_exp_f32_e32 v213, v213
	v_exp_f32_e32 v214, v214
	v_exp_f32_e32 v215, v215
	v_add_f32_e32 v208, 1.0, v208
	v_add_f32_e32 v209, 1.0, v209
	v_add_f32_e32 v210, 1.0, v210
	v_add_f32_e32 v211, 1.0, v211
	v_add_f32_e32 v212, 1.0, v212
	v_add_f32_e32 v213, 1.0, v213
	v_add_f32_e32 v214, 1.0, v214
	v_add_f32_e32 v215, 1.0, v215
	v_rcp_f32_e32 v208, v208
	v_rcp_f32_e32 v209, v209
	v_rcp_f32_e32 v210, v210
	v_rcp_f32_e32 v211, v211
	v_rcp_f32_e32 v212, v212
	v_rcp_f32_e32 v213, v213
	v_rcp_f32_e32 v214, v214
	v_rcp_f32_e32 v215, v215
	v_cvt_pk_bf16_f32 v156, v208, v209
	v_cvt_pk_bf16_f32 v157, v210, v211
	v_cvt_pk_bf16_f32 v158, v212, v213
	v_cvt_pk_bf16_f32 v159, v214, v215
	ds_bpermute_b32 v188, v217, v156
	ds_bpermute_b32 v189, v217, v157
	ds_bpermute_b32 v190, v217, v158
	ds_bpermute_b32 v191, v217, v159
	v_mul_f32_e32 v208, 0xbfb8aa3b, v70
	v_mul_f32_e32 v209, 0xbfb8aa3b, v71
	v_mul_f32_e32 v210, 0xbfb8aa3b, v72
	v_mul_f32_e32 v211, 0xbfb8aa3b, v73
	v_mul_f32_e32 v212, 0xbfb8aa3b, v66
	v_mul_f32_e32 v213, 0xbfb8aa3b, v67
	v_mul_f32_e32 v214, 0xbfb8aa3b, v68
	v_mul_f32_e32 v215, 0xbfb8aa3b, v69
	v_exp_f32_e32 v208, v208
	v_exp_f32_e32 v209, v209
	v_exp_f32_e32 v210, v210
	v_exp_f32_e32 v211, v211
	v_exp_f32_e32 v212, v212
	v_exp_f32_e32 v213, v213
	v_exp_f32_e32 v214, v214
	v_exp_f32_e32 v215, v215
	v_add_f32_e32 v208, 1.0, v208
	v_add_f32_e32 v209, 1.0, v209
	v_add_f32_e32 v210, 1.0, v210
	v_add_f32_e32 v211, 1.0, v211
	v_add_f32_e32 v212, 1.0, v212
	v_add_f32_e32 v213, 1.0, v213
	v_add_f32_e32 v214, 1.0, v214
	v_add_f32_e32 v215, 1.0, v215
	v_rcp_f32_e32 v208, v208
	v_rcp_f32_e32 v209, v209
	v_rcp_f32_e32 v210, v210
	v_rcp_f32_e32 v211, v211
	v_rcp_f32_e32 v212, v212
	v_rcp_f32_e32 v213, v213
	v_rcp_f32_e32 v214, v214
	v_rcp_f32_e32 v215, v215
	v_cvt_pk_bf16_f32 v160, v208, v209
	v_cvt_pk_bf16_f32 v161, v210, v211
	v_cvt_pk_bf16_f32 v162, v212, v213
	v_cvt_pk_bf16_f32 v163, v214, v215
	ds_bpermute_b32 v192, v217, v160
	ds_bpermute_b32 v193, v217, v161
	ds_bpermute_b32 v194, v217, v162
	ds_bpermute_b32 v195, v217, v163
	s_waitcnt lgkmcnt(0)
	global_store_dwordx4 v216, v[180:183], s[10:11] nt
	global_store_dwordx4 v216, v[184:187], s[10:11] offset:256 nt
	global_store_dwordx4 v216, v[188:191], s[20:21] nt
	global_store_dwordx4 v216, v[192:195], s[20:21] offset:256 nt
	s_add_u32 s10, s22, 0x180000
	s_addc_u32 s11, s23, 0
	v_mul_f32_e32 v208, 0xbfb8aa3b, v62
	v_mul_f32_e32 v209, 0xbfb8aa3b, v63
	v_mul_f32_e32 v210, 0xbfb8aa3b, v64
	v_mul_f32_e32 v211, 0xbfb8aa3b, v65
	v_mul_f32_e32 v212, 0xbfb8aa3b, v58
	v_mul_f32_e32 v213, 0xbfb8aa3b, v59
	v_mul_f32_e32 v214, 0xbfb8aa3b, v60
	v_mul_f32_e32 v215, 0xbfb8aa3b, v61
	v_exp_f32_e32 v208, v208
	v_exp_f32_e32 v209, v209
	v_exp_f32_e32 v210, v210
	v_exp_f32_e32 v211, v211
	v_exp_f32_e32 v212, v212
	v_exp_f32_e32 v213, v213
	v_exp_f32_e32 v214, v214
	v_exp_f32_e32 v215, v215
	v_add_f32_e32 v208, 1.0, v208
	v_add_f32_e32 v209, 1.0, v209
	v_add_f32_e32 v210, 1.0, v210
	v_add_f32_e32 v211, 1.0, v211
	v_add_f32_e32 v212, 1.0, v212
	v_add_f32_e32 v213, 1.0, v213
	v_add_f32_e32 v214, 1.0, v214
	v_add_f32_e32 v215, 1.0, v215
	v_rcp_f32_e32 v208, v208
	v_rcp_f32_e32 v209, v209
	v_rcp_f32_e32 v210, v210
	v_rcp_f32_e32 v211, v211
	v_rcp_f32_e32 v212, v212
	v_rcp_f32_e32 v213, v213
	v_rcp_f32_e32 v214, v214
	v_rcp_f32_e32 v215, v215
	v_cvt_pk_bf16_f32 v148, v208, v209
	v_cvt_pk_bf16_f32 v149, v210, v211
	v_cvt_pk_bf16_f32 v150, v212, v213
	v_cvt_pk_bf16_f32 v151, v214, v215
	ds_bpermute_b32 v180, v217, v148
	ds_bpermute_b32 v181, v217, v149
	ds_bpermute_b32 v182, v217, v150
	ds_bpermute_b32 v183, v217, v151
	v_mul_f32_e32 v208, 0xbfb8aa3b, v54
	v_mul_f32_e32 v209, 0xbfb8aa3b, v55
	v_mul_f32_e32 v210, 0xbfb8aa3b, v56
	v_mul_f32_e32 v211, 0xbfb8aa3b, v57
	v_mul_f32_e32 v212, 0xbfb8aa3b, v50
	v_mul_f32_e32 v213, 0xbfb8aa3b, v51
	v_mul_f32_e32 v214, 0xbfb8aa3b, v52
	v_mul_f32_e32 v215, 0xbfb8aa3b, v53
	v_exp_f32_e32 v208, v208
	v_exp_f32_e32 v209, v209
	v_exp_f32_e32 v210, v210
	v_exp_f32_e32 v211, v211
	v_exp_f32_e32 v212, v212
	v_exp_f32_e32 v213, v213
	v_exp_f32_e32 v214, v214
	v_exp_f32_e32 v215, v215
	v_add_f32_e32 v208, 1.0, v208
	v_add_f32_e32 v209, 1.0, v209
	v_add_f32_e32 v210, 1.0, v210
	v_add_f32_e32 v211, 1.0, v211
	v_add_f32_e32 v212, 1.0, v212
	v_add_f32_e32 v213, 1.0, v213
	v_add_f32_e32 v214, 1.0, v214
	v_add_f32_e32 v215, 1.0, v215
	v_rcp_f32_e32 v208, v208
	v_rcp_f32_e32 v209, v209
	v_rcp_f32_e32 v210, v210
	v_rcp_f32_e32 v211, v211
	v_rcp_f32_e32 v212, v212
	v_rcp_f32_e32 v213, v213
	v_rcp_f32_e32 v214, v214
	v_rcp_f32_e32 v215, v215
	v_cvt_pk_bf16_f32 v152, v208, v209
	v_cvt_pk_bf16_f32 v153, v210, v211
	v_cvt_pk_bf16_f32 v154, v212, v213
	v_cvt_pk_bf16_f32 v155, v214, v215
	ds_bpermute_b32 v184, v217, v152
	ds_bpermute_b32 v185, v217, v153
	ds_bpermute_b32 v186, v217, v154
	ds_bpermute_b32 v187, v217, v155
	s_add_u32 s20, s22, 0x1b0000
	s_addc_u32 s21, s23, 0
	v_mul_f32_e32 v208, 0xbfb8aa3b, v46
	v_mul_f32_e32 v209, 0xbfb8aa3b, v47
	v_mul_f32_e32 v210, 0xbfb8aa3b, v48
	v_mul_f32_e32 v211, 0xbfb8aa3b, v49
	v_mul_f32_e32 v212, 0xbfb8aa3b, v42
	v_mul_f32_e32 v213, 0xbfb8aa3b, v43
	v_mul_f32_e32 v214, 0xbfb8aa3b, v44
	v_mul_f32_e32 v215, 0xbfb8aa3b, v45
	v_exp_f32_e32 v208, v208
	v_exp_f32_e32 v209, v209
	v_exp_f32_e32 v210, v210
	v_exp_f32_e32 v211, v211
	v_exp_f32_e32 v212, v212
	v_exp_f32_e32 v213, v213
	v_exp_f32_e32 v214, v214
	v_exp_f32_e32 v215, v215
	v_add_f32_e32 v208, 1.0, v208
	v_add_f32_e32 v209, 1.0, v209
	v_add_f32_e32 v210, 1.0, v210
	v_add_f32_e32 v211, 1.0, v211
	v_add_f32_e32 v212, 1.0, v212
	v_add_f32_e32 v213, 1.0, v213
	v_add_f32_e32 v214, 1.0, v214
	v_add_f32_e32 v215, 1.0, v215
	v_rcp_f32_e32 v208, v208
	v_rcp_f32_e32 v209, v209
	v_rcp_f32_e32 v210, v210
	v_rcp_f32_e32 v211, v211
	v_rcp_f32_e32 v212, v212
	v_rcp_f32_e32 v213, v213
	v_rcp_f32_e32 v214, v214
	v_rcp_f32_e32 v215, v215
	v_cvt_pk_bf16_f32 v156, v208, v209
	v_cvt_pk_bf16_f32 v157, v210, v211
	v_cvt_pk_bf16_f32 v158, v212, v213
	v_cvt_pk_bf16_f32 v159, v214, v215
	ds_bpermute_b32 v188, v217, v156
	ds_bpermute_b32 v189, v217, v157
	ds_bpermute_b32 v190, v217, v158
	ds_bpermute_b32 v191, v217, v159
	v_mul_f32_e32 v208, 0xbfb8aa3b, v38
	v_mul_f32_e32 v209, 0xbfb8aa3b, v39
	v_mul_f32_e32 v210, 0xbfb8aa3b, v40
	v_mul_f32_e32 v211, 0xbfb8aa3b, v41
	v_mul_f32_e32 v212, 0xbfb8aa3b, v34
	v_mul_f32_e32 v213, 0xbfb8aa3b, v35
	v_mul_f32_e32 v214, 0xbfb8aa3b, v36
	v_mul_f32_e32 v215, 0xbfb8aa3b, v37
	v_exp_f32_e32 v208, v208
	v_exp_f32_e32 v209, v209
	v_exp_f32_e32 v210, v210
	v_exp_f32_e32 v211, v211
	v_exp_f32_e32 v212, v212
	v_exp_f32_e32 v213, v213
	v_exp_f32_e32 v214, v214
	v_exp_f32_e32 v215, v215
	v_add_f32_e32 v208, 1.0, v208
	v_add_f32_e32 v209, 1.0, v209
	v_add_f32_e32 v210, 1.0, v210
	v_add_f32_e32 v211, 1.0, v211
	v_add_f32_e32 v212, 1.0, v212
	v_add_f32_e32 v213, 1.0, v213
	v_add_f32_e32 v214, 1.0, v214
	v_add_f32_e32 v215, 1.0, v215
	v_rcp_f32_e32 v208, v208
	v_rcp_f32_e32 v209, v209
	v_rcp_f32_e32 v210, v210
	v_rcp_f32_e32 v211, v211
	v_rcp_f32_e32 v212, v212
	v_rcp_f32_e32 v213, v213
	v_rcp_f32_e32 v214, v214
	v_rcp_f32_e32 v215, v215
	v_cvt_pk_bf16_f32 v160, v208, v209
	v_cvt_pk_bf16_f32 v161, v210, v211
	v_cvt_pk_bf16_f32 v162, v212, v213
	v_cvt_pk_bf16_f32 v163, v214, v215
	ds_bpermute_b32 v192, v217, v160
	ds_bpermute_b32 v193, v217, v161
	ds_bpermute_b32 v194, v217, v162
	ds_bpermute_b32 v195, v217, v163
	s_waitcnt lgkmcnt(0)
	global_store_dwordx4 v216, v[180:183], s[10:11] nt
	global_store_dwordx4 v216, v[184:187], s[10:11] offset:256 nt
	global_store_dwordx4 v216, v[188:191], s[20:21] nt
	global_store_dwordx4 v216, v[192:195], s[20:21] offset:256 nt
	s_add_u32 s10, s22, 0x1e0000
	s_addc_u32 s11, s23, 0
	v_mul_f32_e32 v208, 0xbfb8aa3b, v28
	v_mul_f32_e32 v209, 0xbfb8aa3b, v29
	v_mul_f32_e32 v210, 0xbfb8aa3b, v30
	v_mul_f32_e32 v211, 0xbfb8aa3b, v31
	v_mul_f32_e32 v212, 0xbfb8aa3b, v24
	v_mul_f32_e32 v213, 0xbfb8aa3b, v25
	v_mul_f32_e32 v214, 0xbfb8aa3b, v26
	v_mul_f32_e32 v215, 0xbfb8aa3b, v27
	v_exp_f32_e32 v208, v208
	v_exp_f32_e32 v209, v209
	v_exp_f32_e32 v210, v210
	v_exp_f32_e32 v211, v211
	v_exp_f32_e32 v212, v212
	v_exp_f32_e32 v213, v213
	v_exp_f32_e32 v214, v214
	v_exp_f32_e32 v215, v215
	v_add_f32_e32 v208, 1.0, v208
	v_add_f32_e32 v209, 1.0, v209
	v_add_f32_e32 v210, 1.0, v210
	v_add_f32_e32 v211, 1.0, v211
	v_add_f32_e32 v212, 1.0, v212
	v_add_f32_e32 v213, 1.0, v213
	v_add_f32_e32 v214, 1.0, v214
	v_add_f32_e32 v215, 1.0, v215
	v_rcp_f32_e32 v208, v208
	v_rcp_f32_e32 v209, v209
	v_rcp_f32_e32 v210, v210
	v_rcp_f32_e32 v211, v211
	v_rcp_f32_e32 v212, v212
	v_rcp_f32_e32 v213, v213
	v_rcp_f32_e32 v214, v214
	v_rcp_f32_e32 v215, v215
	v_cvt_pk_bf16_f32 v148, v208, v209
	v_cvt_pk_bf16_f32 v149, v210, v211
	v_cvt_pk_bf16_f32 v150, v212, v213
	v_cvt_pk_bf16_f32 v151, v214, v215
	ds_bpermute_b32 v180, v217, v148
	ds_bpermute_b32 v181, v217, v149
	ds_bpermute_b32 v182, v217, v150
	ds_bpermute_b32 v183, v217, v151
	v_mul_f32_e32 v208, 0xbfb8aa3b, v20
	v_mul_f32_e32 v209, 0xbfb8aa3b, v21
	v_mul_f32_e32 v210, 0xbfb8aa3b, v22
	v_mul_f32_e32 v211, 0xbfb8aa3b, v23
	v_mul_f32_e32 v212, 0xbfb8aa3b, v16
	v_mul_f32_e32 v213, 0xbfb8aa3b, v17
	v_mul_f32_e32 v214, 0xbfb8aa3b, v18
	v_mul_f32_e32 v215, 0xbfb8aa3b, v19
	v_exp_f32_e32 v208, v208
	v_exp_f32_e32 v209, v209
	v_exp_f32_e32 v210, v210
	v_exp_f32_e32 v211, v211
	v_exp_f32_e32 v212, v212
	v_exp_f32_e32 v213, v213
	v_exp_f32_e32 v214, v214
	v_exp_f32_e32 v215, v215
	v_add_f32_e32 v208, 1.0, v208
	v_add_f32_e32 v209, 1.0, v209
	v_add_f32_e32 v210, 1.0, v210
	v_add_f32_e32 v211, 1.0, v211
	v_add_f32_e32 v212, 1.0, v212
	v_add_f32_e32 v213, 1.0, v213
	v_add_f32_e32 v214, 1.0, v214
	v_add_f32_e32 v215, 1.0, v215
	v_rcp_f32_e32 v208, v208
	v_rcp_f32_e32 v209, v209
	v_rcp_f32_e32 v210, v210
	v_rcp_f32_e32 v211, v211
	v_rcp_f32_e32 v212, v212
	v_rcp_f32_e32 v213, v213
	v_rcp_f32_e32 v214, v214
	v_rcp_f32_e32 v215, v215
	v_cvt_pk_bf16_f32 v152, v208, v209
	v_cvt_pk_bf16_f32 v153, v210, v211
	v_cvt_pk_bf16_f32 v154, v212, v213
	v_cvt_pk_bf16_f32 v155, v214, v215
	ds_bpermute_b32 v184, v217, v152
	ds_bpermute_b32 v185, v217, v153
	ds_bpermute_b32 v186, v217, v154
	ds_bpermute_b32 v187, v217, v155
	s_add_u32 s20, s22, 0x210000
	s_addc_u32 s21, s23, 0
	v_mul_f32_e32 v208, 0xbfb8aa3b, v12
	v_mul_f32_e32 v209, 0xbfb8aa3b, v13
	v_mul_f32_e32 v210, 0xbfb8aa3b, v14
	v_mul_f32_e32 v211, 0xbfb8aa3b, v15
	v_mul_f32_e32 v212, 0xbfb8aa3b, v8
	v_mul_f32_e32 v213, 0xbfb8aa3b, v9
	v_mul_f32_e32 v214, 0xbfb8aa3b, v10
	v_mul_f32_e32 v215, 0xbfb8aa3b, v11
	v_exp_f32_e32 v208, v208
	v_exp_f32_e32 v209, v209
	v_exp_f32_e32 v210, v210
	v_exp_f32_e32 v211, v211
	v_exp_f32_e32 v212, v212
	v_exp_f32_e32 v213, v213
	v_exp_f32_e32 v214, v214
	v_exp_f32_e32 v215, v215
	v_add_f32_e32 v208, 1.0, v208
	v_add_f32_e32 v209, 1.0, v209
	v_add_f32_e32 v210, 1.0, v210
	v_add_f32_e32 v211, 1.0, v211
	v_add_f32_e32 v212, 1.0, v212
	v_add_f32_e32 v213, 1.0, v213
	v_add_f32_e32 v214, 1.0, v214
	v_add_f32_e32 v215, 1.0, v215
	v_rcp_f32_e32 v208, v208
	v_rcp_f32_e32 v209, v209
	v_rcp_f32_e32 v210, v210
	v_rcp_f32_e32 v211, v211
	v_rcp_f32_e32 v212, v212
	v_rcp_f32_e32 v213, v213
	v_rcp_f32_e32 v214, v214
	v_rcp_f32_e32 v215, v215
	v_cvt_pk_bf16_f32 v156, v208, v209
	v_cvt_pk_bf16_f32 v157, v210, v211
	v_cvt_pk_bf16_f32 v158, v212, v213
	v_cvt_pk_bf16_f32 v159, v214, v215
	ds_bpermute_b32 v188, v217, v156
	ds_bpermute_b32 v189, v217, v157
	ds_bpermute_b32 v190, v217, v158
	ds_bpermute_b32 v191, v217, v159
	v_mul_f32_e32 v208, 0xbfb8aa3b, v4
	v_mul_f32_e32 v209, 0xbfb8aa3b, v5
	v_mul_f32_e32 v210, 0xbfb8aa3b, v6
	v_mul_f32_e32 v211, 0xbfb8aa3b, v7
	v_mul_f32_e32 v212, 0xbfb8aa3b, v0
	v_mul_f32_e32 v213, 0xbfb8aa3b, v1
	v_mul_f32_e32 v214, 0xbfb8aa3b, v2
	v_mul_f32_e32 v215, 0xbfb8aa3b, v3
	v_exp_f32_e32 v208, v208
	v_exp_f32_e32 v209, v209
	v_exp_f32_e32 v210, v210
	v_exp_f32_e32 v211, v211
	v_exp_f32_e32 v212, v212
	v_exp_f32_e32 v213, v213
	v_exp_f32_e32 v214, v214
	v_exp_f32_e32 v215, v215
	v_add_f32_e32 v208, 1.0, v208
	v_add_f32_e32 v209, 1.0, v209
	v_add_f32_e32 v210, 1.0, v210
	v_add_f32_e32 v211, 1.0, v211
	v_add_f32_e32 v212, 1.0, v212
	v_add_f32_e32 v213, 1.0, v213
	v_add_f32_e32 v214, 1.0, v214
	v_add_f32_e32 v215, 1.0, v215
	v_rcp_f32_e32 v208, v208
	v_rcp_f32_e32 v209, v209
	v_rcp_f32_e32 v210, v210
	v_rcp_f32_e32 v211, v211
	v_rcp_f32_e32 v212, v212
	v_rcp_f32_e32 v213, v213
	v_rcp_f32_e32 v214, v214
	v_rcp_f32_e32 v215, v215
	v_cvt_pk_bf16_f32 v160, v208, v209
	v_cvt_pk_bf16_f32 v161, v210, v211
	v_cvt_pk_bf16_f32 v162, v212, v213
	v_cvt_pk_bf16_f32 v163, v214, v215
	ds_bpermute_b32 v192, v217, v160
	ds_bpermute_b32 v193, v217, v161
	ds_bpermute_b32 v194, v217, v162
	ds_bpermute_b32 v195, v217, v163
	s_waitcnt lgkmcnt(0)
	global_store_dwordx4 v216, v[180:183], s[10:11] nt
	global_store_dwordx4 v216, v[184:187], s[10:11] offset:256 nt
	global_store_dwordx4 v216, v[188:191], s[20:21] nt
	global_store_dwordx4 v216, v[192:195], s[20:21] offset:256 nt
	s_branch .LBB0_364
.Lmain_kv:
	s_bitcmp1_b32 s6, 1
	s_cbranch_scc0 .Lmain_old
	s_cmp_ge_u32 s6, 4
	s_cbranch_scc0 .Lmain_old
	s_mov_b32 s20, 0xcccccccc
	s_mov_b32 s21, 0xcccccccc
	s_mov_b32 s24, 0xf0f0f0f0
	s_mov_b32 s25, 0xf0f0f0f0
	s_mov_b32 s22, 0xaaaaaaaa
	s_mov_b32 s23, 0xaaaaaaaa
	v_mov_b32_e32 v216, 0x5040100
	v_mov_b32_e32 v152, 0x3020706
	v_cndmask_b32_e64 v216, v216, v152, s[22:23]
	v_and_b32_e32 v152, 1, v166
	v_and_b32_e32 v153, 4, v166
	v_lshrrev_b32_e32 v153, 1, v153
	v_and_b32_e32 v154, 2, v166
	v_lshlrev_b32_e32 v154, 1, v154
	v_or3_b32 v152, v152, v153, v154
	v_lshlrev_b32_e32 v217, 4, v152
	v_lshl_add_u32 v217, v32, 3, v217
	v_lshrrev_b32_e32 v153, 3, v166
	v_lshl_add_u32 v217, v153, 11, v217
	s_lshl_b32 s7, s45, 8
	v_add_u32_e32 v217, s7, v217
	s_lshr_b32 s7, s6, 1
	s_lshl_b32 s7, s7, 24
	s_add_u32 s22, s76, s7
	s_addc_u32 s23, s77, 0
	s_add_u32 s22, s22, 0x31e51000
	s_addc_u32 s23, s23, 0
	s_lshr_b32 s7, s31, 3
	s_lshl_b32 s7, s7, 2
	s_and_b32 s13, s6, 1
	s_lshl_b32 s13, s13, 1
	s_add_i32 s7, s7, s13
	s_lshl_b32 s7, s7, 19
	s_and_b32 s13, s31, 7
	s_lshl_b32 s13, s13, 16
	s_add_i32 s7, s7, s13
	s_add_u32 s22, s22, s7
	s_addc_u32 s23, s23, 0
	s_add_u32 s10, s22, 0
	s_addc_u32 s11, s23, 0
	v_cvt_pk_bf16_f32 v148, v126, v127
	v_cvt_pk_bf16_f32 v149, v128, v129
	v_cvt_pk_bf16_f32 v150, v122, v123
	v_cvt_pk_bf16_f32 v151, v124, v125
	s_nop 1
	v_mov_b32_dpp v152, v148 quad_perm:[1,0,3,2] row_mask:0xf bank_mask:0xf
	v_mov_b32_dpp v153, v149 quad_perm:[1,0,3,2] row_mask:0xf bank_mask:0xf
	v_mov_b32_dpp v154, v150 quad_perm:[1,0,3,2] row_mask:0xf bank_mask:0xf
	v_mov_b32_dpp v155, v151 quad_perm:[1,0,3,2] row_mask:0xf bank_mask:0xf
	v_perm_b32 v148, v152, v148, v216
	v_perm_b32 v149, v153, v149, v216
	v_perm_b32 v150, v154, v150, v216
	v_perm_b32 v151, v155, v151, v216
	v_cndmask_b32_e64 v160, v150, v148, s[20:21]
	v_cndmask_b32_e64 v161, v151, v149, s[20:21]
	s_nop 1
	v_mov_b32_dpp v162, v160 quad_perm:[2,3,0,1] row_mask:0xf bank_mask:0xf
	v_mov_b32_dpp v163, v161 quad_perm:[2,3,0,1] row_mask:0xf bank_mask:0xf
	v_cndmask_b32_e64 v156, v148, v162, s[20:21]
	v_cndmask_b32_e64 v157, v162, v150, s[20:21]
	v_cndmask_b32_e64 v158, v149, v163, s[20:21]
	v_cndmask_b32_e64 v159, v163, v151, s[20:21]
	v_cndmask_b32_e64 v160, v158, v156, s[24:25]
	v_cndmask_b32_e64 v161, v159, v157, s[24:25]
	s_nop 1
	v_mov_b32_dpp v162, v160 row_shl:4 row_mask:0xf bank_mask:0x5
	v_mov_b32_dpp v163, v161 row_shl:4 row_mask:0xf bank_mask:0x5
	v_mov_b32_dpp v162, v160 row_shr:4 row_mask:0xf bank_mask:0xa
	v_mov_b32_dpp v163, v161 row_shr:4 row_mask:0xf bank_mask:0xa
	v_cndmask_b32_e64 v208, v156, v162, s[24:25]
	v_cndmask_b32_e64 v209, v157, v163, s[24:25]
	v_cndmask_b32_e64 v210, v162, v158, s[24:25]
	v_cndmask_b32_e64 v211, v163, v159, s[24:25]
	global_store_dwordx4 v217, v[208:211], s[10:11]
	s_add_u32 s10, s22, 0x80000
	s_addc_u32 s11, s23, 0
	v_cvt_pk_bf16_f32 v148, v118, v119
	v_cvt_pk_bf16_f32 v149, v120, v121
	v_cvt_pk_bf16_f32 v150, v114, v115
	v_cvt_pk_bf16_f32 v151, v116, v117
	s_nop 1
	v_mov_b32_dpp v152, v148 quad_perm:[1,0,3,2] row_mask:0xf bank_mask:0xf
	v_mov_b32_dpp v153, v149 quad_perm:[1,0,3,2] row_mask:0xf bank_mask:0xf
	v_mov_b32_dpp v154, v150 quad_perm:[1,0,3,2] row_mask:0xf bank_mask:0xf
	v_mov_b32_dpp v155, v151 quad_perm:[1,0,3,2] row_mask:0xf bank_mask:0xf
	v_perm_b32 v148, v152, v148, v216
	v_perm_b32 v149, v153, v149, v216
	v_perm_b32 v150, v154, v150, v216
	v_perm_b32 v151, v155, v151, v216
	v_cndmask_b32_e64 v160, v150, v148, s[20:21]
	v_cndmask_b32_e64 v161, v151, v149, s[20:21]
	s_nop 1
	v_mov_b32_dpp v162, v160 quad_perm:[2,3,0,1] row_mask:0xf bank_mask:0xf
	v_mov_b32_dpp v163, v161 quad_perm:[2,3,0,1] row_mask:0xf bank_mask:0xf
	v_cndmask_b32_e64 v156, v148, v162, s[20:21]
	v_cndmask_b32_e64 v157, v162, v150, s[20:21]
	v_cndmask_b32_e64 v158, v149, v163, s[20:21]
	v_cndmask_b32_e64 v159, v163, v151, s[20:21]
	v_cndmask_b32_e64 v160, v158, v156, s[24:25]
	v_cndmask_b32_e64 v161, v159, v157, s[24:25]
	s_nop 1
	v_mov_b32_dpp v162, v160 row_shl:4 row_mask:0xf bank_mask:0x5
	v_mov_b32_dpp v163, v161 row_shl:4 row_mask:0xf bank_mask:0x5
	v_mov_b32_dpp v162, v160 row_shr:4 row_mask:0xf bank_mask:0xa
	v_mov_b32_dpp v163, v161 row_shr:4 row_mask:0xf bank_mask:0xa
	v_cndmask_b32_e64 v212, v156, v162, s[24:25]
	v_cndmask_b32_e64 v213, v157, v163, s[24:25]
	v_cndmask_b32_e64 v214, v162, v158, s[24:25]
	v_cndmask_b32_e64 v215, v163, v159, s[24:25]
	global_store_dwordx4 v217, v[212:215], s[10:11]
	s_add_u32 s10, s22, 0x1000
	s_addc_u32 s11, s23, 0
	v_cvt_pk_bf16_f32 v148, v110, v111
	v_cvt_pk_bf16_f32 v149, v112, v113
	v_cvt_pk_bf16_f32 v150, v106, v107
	v_cvt_pk_bf16_f32 v151, v108, v109
	s_nop 1
	v_mov_b32_dpp v152, v148 quad_perm:[1,0,3,2] row_mask:0xf bank_mask:0xf
	v_mov_b32_dpp v153, v149 quad_perm:[1,0,3,2] row_mask:0xf bank_mask:0xf
	v_mov_b32_dpp v154, v150 quad_perm:[1,0,3,2] row_mask:0xf bank_mask:0xf
	v_mov_b32_dpp v155, v151 quad_perm:[1,0,3,2] row_mask:0xf bank_mask:0xf
	v_perm_b32 v148, v152, v148, v216
	v_perm_b32 v149, v153, v149, v216
	v_perm_b32 v150, v154, v150, v216
	v_perm_b32 v151, v155, v151, v216
	v_cndmask_b32_e64 v160, v150, v148, s[20:21]
	v_cndmask_b32_e64 v161, v151, v149, s[20:21]
	s_nop 1
	v_mov_b32_dpp v162, v160 quad_perm:[2,3,0,1] row_mask:0xf bank_mask:0xf
	v_mov_b32_dpp v163, v161 quad_perm:[2,3,0,1] row_mask:0xf bank_mask:0xf
	v_cndmask_b32_e64 v156, v148, v162, s[20:21]
	v_cndmask_b32_e64 v157, v162, v150, s[20:21]
	v_cndmask_b32_e64 v158, v149, v163, s[20:21]
	v_cndmask_b32_e64 v159, v163, v151, s[20:21]
	v_cndmask_b32_e64 v160, v158, v156, s[24:25]
	v_cndmask_b32_e64 v161, v159, v157, s[24:25]
	s_nop 1
	v_mov_b32_dpp v162, v160 row_shl:4 row_mask:0xf bank_mask:0x5
	v_mov_b32_dpp v163, v161 row_shl:4 row_mask:0xf bank_mask:0x5
	v_mov_b32_dpp v162, v160 row_shr:4 row_mask:0xf bank_mask:0xa
	v_mov_b32_dpp v163, v161 row_shr:4 row_mask:0xf bank_mask:0xa
	v_cndmask_b32_e64 v208, v156, v162, s[24:25]
	v_cndmask_b32_e64 v209, v157, v163, s[24:25]
	v_cndmask_b32_e64 v210, v162, v158, s[24:25]
	v_cndmask_b32_e64 v211, v163, v159, s[24:25]
	global_store_dwordx4 v217, v[208:211], s[10:11]
	s_add_u32 s10, s22, 0x81000
	s_addc_u32 s11, s23, 0
	v_cvt_pk_bf16_f32 v148, v102, v103
	v_cvt_pk_bf16_f32 v149, v104, v105
	v_cvt_pk_bf16_f32 v150, v98, v99
	v_cvt_pk_bf16_f32 v151, v100, v101
	s_nop 1
	v_mov_b32_dpp v152, v148 quad_perm:[1,0,3,2] row_mask:0xf bank_mask:0xf
	v_mov_b32_dpp v153, v149 quad_perm:[1,0,3,2] row_mask:0xf bank_mask:0xf
	v_mov_b32_dpp v154, v150 quad_perm:[1,0,3,2] row_mask:0xf bank_mask:0xf
	v_mov_b32_dpp v155, v151 quad_perm:[1,0,3,2] row_mask:0xf bank_mask:0xf
	v_perm_b32 v148, v152, v148, v216
	v_perm_b32 v149, v153, v149, v216
	v_perm_b32 v150, v154, v150, v216
	v_perm_b32 v151, v155, v151, v216
	v_cndmask_b32_e64 v160, v150, v148, s[20:21]
	v_cndmask_b32_e64 v161, v151, v149, s[20:21]
	s_nop 1
	v_mov_b32_dpp v162, v160 quad_perm:[2,3,0,1] row_mask:0xf bank_mask:0xf
	v_mov_b32_dpp v163, v161 quad_perm:[2,3,0,1] row_mask:0xf bank_mask:0xf
	v_cndmask_b32_e64 v156, v148, v162, s[20:21]
	v_cndmask_b32_e64 v157, v162, v150, s[20:21]
	v_cndmask_b32_e64 v158, v149, v163, s[20:21]
	v_cndmask_b32_e64 v159, v163, v151, s[20:21]
	v_cndmask_b32_e64 v160, v158, v156, s[24:25]
	v_cndmask_b32_e64 v161, v159, v157, s[24:25]
	s_nop 1
	v_mov_b32_dpp v162, v160 row_shl:4 row_mask:0xf bank_mask:0x5
	v_mov_b32_dpp v163, v161 row_shl:4 row_mask:0xf bank_mask:0x5
	v_mov_b32_dpp v162, v160 row_shr:4 row_mask:0xf bank_mask:0xa
	v_mov_b32_dpp v163, v161 row_shr:4 row_mask:0xf bank_mask:0xa
	v_cndmask_b32_e64 v212, v156, v162, s[24:25]
	v_cndmask_b32_e64 v213, v157, v163, s[24:25]
	v_cndmask_b32_e64 v214, v162, v158, s[24:25]
	v_cndmask_b32_e64 v215, v163, v159, s[24:25]
	global_store_dwordx4 v217, v[212:215], s[10:11]
	s_add_u32 s10, s22, 0x2000
	s_addc_u32 s11, s23, 0
	v_cvt_pk_bf16_f32 v148, v94, v95
	v_cvt_pk_bf16_f32 v149, v96, v97
	v_cvt_pk_bf16_f32 v150, v90, v91
	v_cvt_pk_bf16_f32 v151, v92, v93
	s_nop 1
	v_mov_b32_dpp v152, v148 quad_perm:[1,0,3,2] row_mask:0xf bank_mask:0xf
	v_mov_b32_dpp v153, v149 quad_perm:[1,0,3,2] row_mask:0xf bank_mask:0xf
	v_mov_b32_dpp v154, v150 quad_perm:[1,0,3,2] row_mask:0xf bank_mask:0xf
	v_mov_b32_dpp v155, v151 quad_perm:[1,0,3,2] row_mask:0xf bank_mask:0xf
	v_perm_b32 v148, v152, v148, v216
	v_perm_b32 v149, v153, v149, v216
	v_perm_b32 v150, v154, v150, v216
	v_perm_b32 v151, v155, v151, v216
	v_cndmask_b32_e64 v160, v150, v148, s[20:21]
	v_cndmask_b32_e64 v161, v151, v149, s[20:21]
	s_nop 1
	v_mov_b32_dpp v162, v160 quad_perm:[2,3,0,1] row_mask:0xf bank_mask:0xf
	v_mov_b32_dpp v163, v161 quad_perm:[2,3,0,1] row_mask:0xf bank_mask:0xf
	v_cndmask_b32_e64 v156, v148, v162, s[20:21]
	v_cndmask_b32_e64 v157, v162, v150, s[20:21]
	v_cndmask_b32_e64 v158, v149, v163, s[20:21]
	v_cndmask_b32_e64 v159, v163, v151, s[20:21]
	v_cndmask_b32_e64 v160, v158, v156, s[24:25]
	v_cndmask_b32_e64 v161, v159, v157, s[24:25]
	s_nop 1
	v_mov_b32_dpp v162, v160 row_shl:4 row_mask:0xf bank_mask:0x5
	v_mov_b32_dpp v163, v161 row_shl:4 row_mask:0xf bank_mask:0x5
	v_mov_b32_dpp v162, v160 row_shr:4 row_mask:0xf bank_mask:0xa
	v_mov_b32_dpp v163, v161 row_shr:4 row_mask:0xf bank_mask:0xa
	v_cndmask_b32_e64 v208, v156, v162, s[24:25]
	v_cndmask_b32_e64 v209, v157, v163, s[24:25]
	v_cndmask_b32_e64 v210, v162, v158, s[24:25]
	v_cndmask_b32_e64 v211, v163, v159, s[24:25]
	global_store_dwordx4 v217, v[208:211], s[10:11]
	s_add_u32 s10, s22, 0x82000
	s_addc_u32 s11, s23, 0
	v_cvt_pk_bf16_f32 v148, v86, v87
	v_cvt_pk_bf16_f32 v149, v88, v89
	v_cvt_pk_bf16_f32 v150, v82, v83
	v_cvt_pk_bf16_f32 v151, v84, v85
	s_nop 1
	v_mov_b32_dpp v152, v148 quad_perm:[1,0,3,2] row_mask:0xf bank_mask:0xf
	v_mov_b32_dpp v153, v149 quad_perm:[1,0,3,2] row_mask:0xf bank_mask:0xf
	v_mov_b32_dpp v154, v150 quad_perm:[1,0,3,2] row_mask:0xf bank_mask:0xf
	v_mov_b32_dpp v155, v151 quad_perm:[1,0,3,2] row_mask:0xf bank_mask:0xf
	v_perm_b32 v148, v152, v148, v216
	v_perm_b32 v149, v153, v149, v216
	v_perm_b32 v150, v154, v150, v216
	v_perm_b32 v151, v155, v151, v216
	v_cndmask_b32_e64 v160, v150, v148, s[20:21]
	v_cndmask_b32_e64 v161, v151, v149, s[20:21]
	s_nop 1
	v_mov_b32_dpp v162, v160 quad_perm:[2,3,0,1] row_mask:0xf bank_mask:0xf
	v_mov_b32_dpp v163, v161 quad_perm:[2,3,0,1] row_mask:0xf bank_mask:0xf
	v_cndmask_b32_e64 v156, v148, v162, s[20:21]
	v_cndmask_b32_e64 v157, v162, v150, s[20:21]
	v_cndmask_b32_e64 v158, v149, v163, s[20:21]
	v_cndmask_b32_e64 v159, v163, v151, s[20:21]
	v_cndmask_b32_e64 v160, v158, v156, s[24:25]
	v_cndmask_b32_e64 v161, v159, v157, s[24:25]
	s_nop 1
	v_mov_b32_dpp v162, v160 row_shl:4 row_mask:0xf bank_mask:0x5
	v_mov_b32_dpp v163, v161 row_shl:4 row_mask:0xf bank_mask:0x5
	v_mov_b32_dpp v162, v160 row_shr:4 row_mask:0xf bank_mask:0xa
	v_mov_b32_dpp v163, v161 row_shr:4 row_mask:0xf bank_mask:0xa
	v_cndmask_b32_e64 v212, v156, v162, s[24:25]
	v_cndmask_b32_e64 v213, v157, v163, s[24:25]
	v_cndmask_b32_e64 v214, v162, v158, s[24:25]
	v_cndmask_b32_e64 v215, v163, v159, s[24:25]
	global_store_dwordx4 v217, v[212:215], s[10:11]
	s_add_u32 s10, s22, 0x3000
	s_addc_u32 s11, s23, 0
	v_cvt_pk_bf16_f32 v148, v78, v79
	v_cvt_pk_bf16_f32 v149, v80, v81
	v_cvt_pk_bf16_f32 v150, v74, v75
	v_cvt_pk_bf16_f32 v151, v76, v77
	s_nop 1
	v_mov_b32_dpp v152, v148 quad_perm:[1,0,3,2] row_mask:0xf bank_mask:0xf
	v_mov_b32_dpp v153, v149 quad_perm:[1,0,3,2] row_mask:0xf bank_mask:0xf
	v_mov_b32_dpp v154, v150 quad_perm:[1,0,3,2] row_mask:0xf bank_mask:0xf
	v_mov_b32_dpp v155, v151 quad_perm:[1,0,3,2] row_mask:0xf bank_mask:0xf
	v_perm_b32 v148, v152, v148, v216
	v_perm_b32 v149, v153, v149, v216
	v_perm_b32 v150, v154, v150, v216
	v_perm_b32 v151, v155, v151, v216
	v_cndmask_b32_e64 v160, v150, v148, s[20:21]
	v_cndmask_b32_e64 v161, v151, v149, s[20:21]
	s_nop 1
	v_mov_b32_dpp v162, v160 quad_perm:[2,3,0,1] row_mask:0xf bank_mask:0xf
	v_mov_b32_dpp v163, v161 quad_perm:[2,3,0,1] row_mask:0xf bank_mask:0xf
	v_cndmask_b32_e64 v156, v148, v162, s[20:21]
	v_cndmask_b32_e64 v157, v162, v150, s[20:21]
	v_cndmask_b32_e64 v158, v149, v163, s[20:21]
	v_cndmask_b32_e64 v159, v163, v151, s[20:21]
	v_cndmask_b32_e64 v160, v158, v156, s[24:25]
	v_cndmask_b32_e64 v161, v159, v157, s[24:25]
	s_nop 1
	v_mov_b32_dpp v162, v160 row_shl:4 row_mask:0xf bank_mask:0x5
	v_mov_b32_dpp v163, v161 row_shl:4 row_mask:0xf bank_mask:0x5
	v_mov_b32_dpp v162, v160 row_shr:4 row_mask:0xf bank_mask:0xa
	v_mov_b32_dpp v163, v161 row_shr:4 row_mask:0xf bank_mask:0xa
	v_cndmask_b32_e64 v208, v156, v162, s[24:25]
	v_cndmask_b32_e64 v209, v157, v163, s[24:25]
	v_cndmask_b32_e64 v210, v162, v158, s[24:25]
	v_cndmask_b32_e64 v211, v163, v159, s[24:25]
	global_store_dwordx4 v217, v[208:211], s[10:11]
	s_add_u32 s10, s22, 0x83000
	s_addc_u32 s11, s23, 0
	v_cvt_pk_bf16_f32 v148, v70, v71
	v_cvt_pk_bf16_f32 v149, v72, v73
	v_cvt_pk_bf16_f32 v150, v66, v67
	v_cvt_pk_bf16_f32 v151, v68, v69
	s_nop 1
	v_mov_b32_dpp v152, v148 quad_perm:[1,0,3,2] row_mask:0xf bank_mask:0xf
	v_mov_b32_dpp v153, v149 quad_perm:[1,0,3,2] row_mask:0xf bank_mask:0xf
	v_mov_b32_dpp v154, v150 quad_perm:[1,0,3,2] row_mask:0xf bank_mask:0xf
	v_mov_b32_dpp v155, v151 quad_perm:[1,0,3,2] row_mask:0xf bank_mask:0xf
	v_perm_b32 v148, v152, v148, v216
	v_perm_b32 v149, v153, v149, v216
	v_perm_b32 v150, v154, v150, v216
	v_perm_b32 v151, v155, v151, v216
	v_cndmask_b32_e64 v160, v150, v148, s[20:21]
	v_cndmask_b32_e64 v161, v151, v149, s[20:21]
	s_nop 1
	v_mov_b32_dpp v162, v160 quad_perm:[2,3,0,1] row_mask:0xf bank_mask:0xf
	v_mov_b32_dpp v163, v161 quad_perm:[2,3,0,1] row_mask:0xf bank_mask:0xf
	v_cndmask_b32_e64 v156, v148, v162, s[20:21]
	v_cndmask_b32_e64 v157, v162, v150, s[20:21]
	v_cndmask_b32_e64 v158, v149, v163, s[20:21]
	v_cndmask_b32_e64 v159, v163, v151, s[20:21]
	v_cndmask_b32_e64 v160, v158, v156, s[24:25]
	v_cndmask_b32_e64 v161, v159, v157, s[24:25]
	s_nop 1
	v_mov_b32_dpp v162, v160 row_shl:4 row_mask:0xf bank_mask:0x5
	v_mov_b32_dpp v163, v161 row_shl:4 row_mask:0xf bank_mask:0x5
	v_mov_b32_dpp v162, v160 row_shr:4 row_mask:0xf bank_mask:0xa
	v_mov_b32_dpp v163, v161 row_shr:4 row_mask:0xf bank_mask:0xa
	v_cndmask_b32_e64 v212, v156, v162, s[24:25]
	v_cndmask_b32_e64 v213, v157, v163, s[24:25]
	v_cndmask_b32_e64 v214, v162, v158, s[24:25]
	v_cndmask_b32_e64 v215, v163, v159, s[24:25]
	global_store_dwordx4 v217, v[212:215], s[10:11]
	s_add_u32 s10, s22, 0x8000
	s_addc_u32 s11, s23, 0
	v_cvt_pk_bf16_f32 v148, v62, v63
	v_cvt_pk_bf16_f32 v149, v64, v65
	v_cvt_pk_bf16_f32 v150, v58, v59
	v_cvt_pk_bf16_f32 v151, v60, v61
	s_nop 1
	v_mov_b32_dpp v152, v148 quad_perm:[1,0,3,2] row_mask:0xf bank_mask:0xf
	v_mov_b32_dpp v153, v149 quad_perm:[1,0,3,2] row_mask:0xf bank_mask:0xf
	v_mov_b32_dpp v154, v150 quad_perm:[1,0,3,2] row_mask:0xf bank_mask:0xf
	v_mov_b32_dpp v155, v151 quad_perm:[1,0,3,2] row_mask:0xf bank_mask:0xf
	v_perm_b32 v148, v152, v148, v216
	v_perm_b32 v149, v153, v149, v216
	v_perm_b32 v150, v154, v150, v216
	v_perm_b32 v151, v155, v151, v216
	v_cndmask_b32_e64 v160, v150, v148, s[20:21]
	v_cndmask_b32_e64 v161, v151, v149, s[20:21]
	s_nop 1
	v_mov_b32_dpp v162, v160 quad_perm:[2,3,0,1] row_mask:0xf bank_mask:0xf
	v_mov_b32_dpp v163, v161 quad_perm:[2,3,0,1] row_mask:0xf bank_mask:0xf
	v_cndmask_b32_e64 v156, v148, v162, s[20:21]
	v_cndmask_b32_e64 v157, v162, v150, s[20:21]
	v_cndmask_b32_e64 v158, v149, v163, s[20:21]
	v_cndmask_b32_e64 v159, v163, v151, s[20:21]
	v_cndmask_b32_e64 v160, v158, v156, s[24:25]
	v_cndmask_b32_e64 v161, v159, v157, s[24:25]
	s_nop 1
	v_mov_b32_dpp v162, v160 row_shl:4 row_mask:0xf bank_mask:0x5
	v_mov_b32_dpp v163, v161 row_shl:4 row_mask:0xf bank_mask:0x5
	v_mov_b32_dpp v162, v160 row_shr:4 row_mask:0xf bank_mask:0xa
	v_mov_b32_dpp v163, v161 row_shr:4 row_mask:0xf bank_mask:0xa
	v_cndmask_b32_e64 v208, v156, v162, s[24:25]
	v_cndmask_b32_e64 v209, v157, v163, s[24:25]
	v_cndmask_b32_e64 v210, v162, v158, s[24:25]
	v_cndmask_b32_e64 v211, v163, v159, s[24:25]
	global_store_dwordx4 v217, v[208:211], s[10:11]
	s_add_u32 s10, s22, 0x88000
	s_addc_u32 s11, s23, 0
	v_cvt_pk_bf16_f32 v148, v54, v55
	v_cvt_pk_bf16_f32 v149, v56, v57
	v_cvt_pk_bf16_f32 v150, v50, v51
	v_cvt_pk_bf16_f32 v151, v52, v53
	s_nop 1
	v_mov_b32_dpp v152, v148 quad_perm:[1,0,3,2] row_mask:0xf bank_mask:0xf
	v_mov_b32_dpp v153, v149 quad_perm:[1,0,3,2] row_mask:0xf bank_mask:0xf
	v_mov_b32_dpp v154, v150 quad_perm:[1,0,3,2] row_mask:0xf bank_mask:0xf
	v_mov_b32_dpp v155, v151 quad_perm:[1,0,3,2] row_mask:0xf bank_mask:0xf
	v_perm_b32 v148, v152, v148, v216
	v_perm_b32 v149, v153, v149, v216
	v_perm_b32 v150, v154, v150, v216
	v_perm_b32 v151, v155, v151, v216
	v_cndmask_b32_e64 v160, v150, v148, s[20:21]
	v_cndmask_b32_e64 v161, v151, v149, s[20:21]
	s_nop 1
	v_mov_b32_dpp v162, v160 quad_perm:[2,3,0,1] row_mask:0xf bank_mask:0xf
	v_mov_b32_dpp v163, v161 quad_perm:[2,3,0,1] row_mask:0xf bank_mask:0xf
	v_cndmask_b32_e64 v156, v148, v162, s[20:21]
	v_cndmask_b32_e64 v157, v162, v150, s[20:21]
	v_cndmask_b32_e64 v158, v149, v163, s[20:21]
	v_cndmask_b32_e64 v159, v163, v151, s[20:21]
	v_cndmask_b32_e64 v160, v158, v156, s[24:25]
	v_cndmask_b32_e64 v161, v159, v157, s[24:25]
	s_nop 1
	v_mov_b32_dpp v162, v160 row_shl:4 row_mask:0xf bank_mask:0x5
	v_mov_b32_dpp v163, v161 row_shl:4 row_mask:0xf bank_mask:0x5
	v_mov_b32_dpp v162, v160 row_shr:4 row_mask:0xf bank_mask:0xa
	v_mov_b32_dpp v163, v161 row_shr:4 row_mask:0xf bank_mask:0xa
	v_cndmask_b32_e64 v212, v156, v162, s[24:25]
	v_cndmask_b32_e64 v213, v157, v163, s[24:25]
	v_cndmask_b32_e64 v214, v162, v158, s[24:25]
	v_cndmask_b32_e64 v215, v163, v159, s[24:25]
	global_store_dwordx4 v217, v[212:215], s[10:11]
	s_add_u32 s10, s22, 0x9000
	s_addc_u32 s11, s23, 0
	v_cvt_pk_bf16_f32 v148, v46, v47
	v_cvt_pk_bf16_f32 v149, v48, v49
	v_cvt_pk_bf16_f32 v150, v42, v43
	v_cvt_pk_bf16_f32 v151, v44, v45
	s_nop 1
	v_mov_b32_dpp v152, v148 quad_perm:[1,0,3,2] row_mask:0xf bank_mask:0xf
	v_mov_b32_dpp v153, v149 quad_perm:[1,0,3,2] row_mask:0xf bank_mask:0xf
	v_mov_b32_dpp v154, v150 quad_perm:[1,0,3,2] row_mask:0xf bank_mask:0xf
	v_mov_b32_dpp v155, v151 quad_perm:[1,0,3,2] row_mask:0xf bank_mask:0xf
	v_perm_b32 v148, v152, v148, v216
	v_perm_b32 v149, v153, v149, v216
	v_perm_b32 v150, v154, v150, v216
	v_perm_b32 v151, v155, v151, v216
	v_cndmask_b32_e64 v160, v150, v148, s[20:21]
	v_cndmask_b32_e64 v161, v151, v149, s[20:21]
	s_nop 1
	v_mov_b32_dpp v162, v160 quad_perm:[2,3,0,1] row_mask:0xf bank_mask:0xf
	v_mov_b32_dpp v163, v161 quad_perm:[2,3,0,1] row_mask:0xf bank_mask:0xf
	v_cndmask_b32_e64 v156, v148, v162, s[20:21]
	v_cndmask_b32_e64 v157, v162, v150, s[20:21]
	v_cndmask_b32_e64 v158, v149, v163, s[20:21]
	v_cndmask_b32_e64 v159, v163, v151, s[20:21]
	v_cndmask_b32_e64 v160, v158, v156, s[24:25]
	v_cndmask_b32_e64 v161, v159, v157, s[24:25]
	s_nop 1
	v_mov_b32_dpp v162, v160 row_shl:4 row_mask:0xf bank_mask:0x5
	v_mov_b32_dpp v163, v161 row_shl:4 row_mask:0xf bank_mask:0x5
	v_mov_b32_dpp v162, v160 row_shr:4 row_mask:0xf bank_mask:0xa
	v_mov_b32_dpp v163, v161 row_shr:4 row_mask:0xf bank_mask:0xa
	v_cndmask_b32_e64 v208, v156, v162, s[24:25]
	v_cndmask_b32_e64 v209, v157, v163, s[24:25]
	v_cndmask_b32_e64 v210, v162, v158, s[24:25]
	v_cndmask_b32_e64 v211, v163, v159, s[24:25]
	global_store_dwordx4 v217, v[208:211], s[10:11]
	s_add_u32 s10, s22, 0x89000
	s_addc_u32 s11, s23, 0
	v_cvt_pk_bf16_f32 v148, v38, v39
	v_cvt_pk_bf16_f32 v149, v40, v41
	v_cvt_pk_bf16_f32 v150, v34, v35
	v_cvt_pk_bf16_f32 v151, v36, v37
	s_nop 1
	v_mov_b32_dpp v152, v148 quad_perm:[1,0,3,2] row_mask:0xf bank_mask:0xf
	v_mov_b32_dpp v153, v149 quad_perm:[1,0,3,2] row_mask:0xf bank_mask:0xf
	v_mov_b32_dpp v154, v150 quad_perm:[1,0,3,2] row_mask:0xf bank_mask:0xf
	v_mov_b32_dpp v155, v151 quad_perm:[1,0,3,2] row_mask:0xf bank_mask:0xf
	v_perm_b32 v148, v152, v148, v216
	v_perm_b32 v149, v153, v149, v216
	v_perm_b32 v150, v154, v150, v216
	v_perm_b32 v151, v155, v151, v216
	v_cndmask_b32_e64 v160, v150, v148, s[20:21]
	v_cndmask_b32_e64 v161, v151, v149, s[20:21]
	s_nop 1
	v_mov_b32_dpp v162, v160 quad_perm:[2,3,0,1] row_mask:0xf bank_mask:0xf
	v_mov_b32_dpp v163, v161 quad_perm:[2,3,0,1] row_mask:0xf bank_mask:0xf
	v_cndmask_b32_e64 v156, v148, v162, s[20:21]
	v_cndmask_b32_e64 v157, v162, v150, s[20:21]
	v_cndmask_b32_e64 v158, v149, v163, s[20:21]
	v_cndmask_b32_e64 v159, v163, v151, s[20:21]
	v_cndmask_b32_e64 v160, v158, v156, s[24:25]
	v_cndmask_b32_e64 v161, v159, v157, s[24:25]
	s_nop 1
	v_mov_b32_dpp v162, v160 row_shl:4 row_mask:0xf bank_mask:0x5
	v_mov_b32_dpp v163, v161 row_shl:4 row_mask:0xf bank_mask:0x5
	v_mov_b32_dpp v162, v160 row_shr:4 row_mask:0xf bank_mask:0xa
	v_mov_b32_dpp v163, v161 row_shr:4 row_mask:0xf bank_mask:0xa
	v_cndmask_b32_e64 v212, v156, v162, s[24:25]
	v_cndmask_b32_e64 v213, v157, v163, s[24:25]
	v_cndmask_b32_e64 v214, v162, v158, s[24:25]
	v_cndmask_b32_e64 v215, v163, v159, s[24:25]
	global_store_dwordx4 v217, v[212:215], s[10:11]
	s_add_u32 s10, s22, 0xa000
	s_addc_u32 s11, s23, 0
	v_cvt_pk_bf16_f32 v148, v28, v29
	v_cvt_pk_bf16_f32 v149, v30, v31
	v_cvt_pk_bf16_f32 v150, v24, v25
	v_cvt_pk_bf16_f32 v151, v26, v27
	s_nop 1
	v_mov_b32_dpp v152, v148 quad_perm:[1,0,3,2] row_mask:0xf bank_mask:0xf
	v_mov_b32_dpp v153, v149 quad_perm:[1,0,3,2] row_mask:0xf bank_mask:0xf
	v_mov_b32_dpp v154, v150 quad_perm:[1,0,3,2] row_mask:0xf bank_mask:0xf
	v_mov_b32_dpp v155, v151 quad_perm:[1,0,3,2] row_mask:0xf bank_mask:0xf
	v_perm_b32 v148, v152, v148, v216
	v_perm_b32 v149, v153, v149, v216
	v_perm_b32 v150, v154, v150, v216
	v_perm_b32 v151, v155, v151, v216
	v_cndmask_b32_e64 v160, v150, v148, s[20:21]
	v_cndmask_b32_e64 v161, v151, v149, s[20:21]
	s_nop 1
	v_mov_b32_dpp v162, v160 quad_perm:[2,3,0,1] row_mask:0xf bank_mask:0xf
	v_mov_b32_dpp v163, v161 quad_perm:[2,3,0,1] row_mask:0xf bank_mask:0xf
	v_cndmask_b32_e64 v156, v148, v162, s[20:21]
	v_cndmask_b32_e64 v157, v162, v150, s[20:21]
	v_cndmask_b32_e64 v158, v149, v163, s[20:21]
	v_cndmask_b32_e64 v159, v163, v151, s[20:21]
	v_cndmask_b32_e64 v160, v158, v156, s[24:25]
	v_cndmask_b32_e64 v161, v159, v157, s[24:25]
	s_nop 1
	v_mov_b32_dpp v162, v160 row_shl:4 row_mask:0xf bank_mask:0x5
	v_mov_b32_dpp v163, v161 row_shl:4 row_mask:0xf bank_mask:0x5
	v_mov_b32_dpp v162, v160 row_shr:4 row_mask:0xf bank_mask:0xa
	v_mov_b32_dpp v163, v161 row_shr:4 row_mask:0xf bank_mask:0xa
	v_cndmask_b32_e64 v208, v156, v162, s[24:25]
	v_cndmask_b32_e64 v209, v157, v163, s[24:25]
	v_cndmask_b32_e64 v210, v162, v158, s[24:25]
	v_cndmask_b32_e64 v211, v163, v159, s[24:25]
	global_store_dwordx4 v217, v[208:211], s[10:11]
	s_add_u32 s10, s22, 0x8a000
	s_addc_u32 s11, s23, 0
	v_cvt_pk_bf16_f32 v148, v20, v21
	v_cvt_pk_bf16_f32 v149, v22, v23
	v_cvt_pk_bf16_f32 v150, v16, v17
	v_cvt_pk_bf16_f32 v151, v18, v19
	s_nop 1
	v_mov_b32_dpp v152, v148 quad_perm:[1,0,3,2] row_mask:0xf bank_mask:0xf
	v_mov_b32_dpp v153, v149 quad_perm:[1,0,3,2] row_mask:0xf bank_mask:0xf
	v_mov_b32_dpp v154, v150 quad_perm:[1,0,3,2] row_mask:0xf bank_mask:0xf
	v_mov_b32_dpp v155, v151 quad_perm:[1,0,3,2] row_mask:0xf bank_mask:0xf
	v_perm_b32 v148, v152, v148, v216
	v_perm_b32 v149, v153, v149, v216
	v_perm_b32 v150, v154, v150, v216
	v_perm_b32 v151, v155, v151, v216
	v_cndmask_b32_e64 v160, v150, v148, s[20:21]
	v_cndmask_b32_e64 v161, v151, v149, s[20:21]
	s_nop 1
	v_mov_b32_dpp v162, v160 quad_perm:[2,3,0,1] row_mask:0xf bank_mask:0xf
	v_mov_b32_dpp v163, v161 quad_perm:[2,3,0,1] row_mask:0xf bank_mask:0xf
	v_cndmask_b32_e64 v156, v148, v162, s[20:21]
	v_cndmask_b32_e64 v157, v162, v150, s[20:21]
	v_cndmask_b32_e64 v158, v149, v163, s[20:21]
	v_cndmask_b32_e64 v159, v163, v151, s[20:21]
	v_cndmask_b32_e64 v160, v158, v156, s[24:25]
	v_cndmask_b32_e64 v161, v159, v157, s[24:25]
	s_nop 1
	v_mov_b32_dpp v162, v160 row_shl:4 row_mask:0xf bank_mask:0x5
	v_mov_b32_dpp v163, v161 row_shl:4 row_mask:0xf bank_mask:0x5
	v_mov_b32_dpp v162, v160 row_shr:4 row_mask:0xf bank_mask:0xa
	v_mov_b32_dpp v163, v161 row_shr:4 row_mask:0xf bank_mask:0xa
	v_cndmask_b32_e64 v212, v156, v162, s[24:25]
	v_cndmask_b32_e64 v213, v157, v163, s[24:25]
	v_cndmask_b32_e64 v214, v162, v158, s[24:25]
	v_cndmask_b32_e64 v215, v163, v159, s[24:25]
	global_store_dwordx4 v217, v[212:215], s[10:11]
	s_add_u32 s10, s22, 0xb000
	s_addc_u32 s11, s23, 0
	v_cvt_pk_bf16_f32 v148, v12, v13
	v_cvt_pk_bf16_f32 v149, v14, v15
	v_cvt_pk_bf16_f32 v150, v8, v9
	v_cvt_pk_bf16_f32 v151, v10, v11
	s_nop 1
	v_mov_b32_dpp v152, v148 quad_perm:[1,0,3,2] row_mask:0xf bank_mask:0xf
	v_mov_b32_dpp v153, v149 quad_perm:[1,0,3,2] row_mask:0xf bank_mask:0xf
	v_mov_b32_dpp v154, v150 quad_perm:[1,0,3,2] row_mask:0xf bank_mask:0xf
	v_mov_b32_dpp v155, v151 quad_perm:[1,0,3,2] row_mask:0xf bank_mask:0xf
	v_perm_b32 v148, v152, v148, v216
	v_perm_b32 v149, v153, v149, v216
	v_perm_b32 v150, v154, v150, v216
	v_perm_b32 v151, v155, v151, v216
	v_cndmask_b32_e64 v160, v150, v148, s[20:21]
	v_cndmask_b32_e64 v161, v151, v149, s[20:21]
	s_nop 1
	v_mov_b32_dpp v162, v160 quad_perm:[2,3,0,1] row_mask:0xf bank_mask:0xf
	v_mov_b32_dpp v163, v161 quad_perm:[2,3,0,1] row_mask:0xf bank_mask:0xf
	v_cndmask_b32_e64 v156, v148, v162, s[20:21]
	v_cndmask_b32_e64 v157, v162, v150, s[20:21]
	v_cndmask_b32_e64 v158, v149, v163, s[20:21]
	v_cndmask_b32_e64 v159, v163, v151, s[20:21]
	v_cndmask_b32_e64 v160, v158, v156, s[24:25]
	v_cndmask_b32_e64 v161, v159, v157, s[24:25]
	s_nop 1
	v_mov_b32_dpp v162, v160 row_shl:4 row_mask:0xf bank_mask:0x5
	v_mov_b32_dpp v163, v161 row_shl:4 row_mask:0xf bank_mask:0x5
	v_mov_b32_dpp v162, v160 row_shr:4 row_mask:0xf bank_mask:0xa
	v_mov_b32_dpp v163, v161 row_shr:4 row_mask:0xf bank_mask:0xa
	v_cndmask_b32_e64 v208, v156, v162, s[24:25]
	v_cndmask_b32_e64 v209, v157, v163, s[24:25]
	v_cndmask_b32_e64 v210, v162, v158, s[24:25]
	v_cndmask_b32_e64 v211, v163, v159, s[24:25]
	global_store_dwordx4 v217, v[208:211], s[10:11]
	s_add_u32 s10, s22, 0x8b000
	s_addc_u32 s11, s23, 0
	v_cvt_pk_bf16_f32 v148, v4, v5
	v_cvt_pk_bf16_f32 v149, v6, v7
	v_cvt_pk_bf16_f32 v150, v0, v1
	v_cvt_pk_bf16_f32 v151, v2, v3
	s_nop 1
	v_mov_b32_dpp v152, v148 quad_perm:[1,0,3,2] row_mask:0xf bank_mask:0xf
	v_mov_b32_dpp v153, v149 quad_perm:[1,0,3,2] row_mask:0xf bank_mask:0xf
	v_mov_b32_dpp v154, v150 quad_perm:[1,0,3,2] row_mask:0xf bank_mask:0xf
	v_mov_b32_dpp v155, v151 quad_perm:[1,0,3,2] row_mask:0xf bank_mask:0xf
	v_perm_b32 v148, v152, v148, v216
	v_perm_b32 v149, v153, v149, v216
	v_perm_b32 v150, v154, v150, v216
	v_perm_b32 v151, v155, v151, v216
	v_cndmask_b32_e64 v160, v150, v148, s[20:21]
	v_cndmask_b32_e64 v161, v151, v149, s[20:21]
	s_nop 1
	v_mov_b32_dpp v162, v160 quad_perm:[2,3,0,1] row_mask:0xf bank_mask:0xf
	v_mov_b32_dpp v163, v161 quad_perm:[2,3,0,1] row_mask:0xf bank_mask:0xf
	v_cndmask_b32_e64 v156, v148, v162, s[20:21]
	v_cndmask_b32_e64 v157, v162, v150, s[20:21]
	v_cndmask_b32_e64 v158, v149, v163, s[20:21]
	v_cndmask_b32_e64 v159, v163, v151, s[20:21]
	v_cndmask_b32_e64 v160, v158, v156, s[24:25]
	v_cndmask_b32_e64 v161, v159, v157, s[24:25]
	s_nop 1
	v_mov_b32_dpp v162, v160 row_shl:4 row_mask:0xf bank_mask:0x5
	v_mov_b32_dpp v163, v161 row_shl:4 row_mask:0xf bank_mask:0x5
	v_mov_b32_dpp v162, v160 row_shr:4 row_mask:0xf bank_mask:0xa
	v_mov_b32_dpp v163, v161 row_shr:4 row_mask:0xf bank_mask:0xa
	v_cndmask_b32_e64 v212, v156, v162, s[24:25]
	v_cndmask_b32_e64 v213, v157, v163, s[24:25]
	v_cndmask_b32_e64 v214, v162, v158, s[24:25]
	v_cndmask_b32_e64 v215, v163, v159, s[24:25]
	global_store_dwordx4 v217, v[212:215], s[10:11]
	s_branch .LBB0_364
